# residual GEMM epilogues: the 4x9 serialized adaLN gate loads (wait after each) issued together per chain with counted vmcnt waits
# speedup vs baseline: 1.0316x; 1.0184x over previous
.LBB0_411:
	v_lshl_or_b32 v168, s76, 8, v198
	v_add_u32_e32 v156, 0x800, v168
	v_ashrrev_i32_e32 v157, 31, v156
	v_lshlrev_b64 v[160:161], 2, v[156:157]
	s_ashr_i32 s49, s46, 3
	v_lshl_add_u64 v[164:165], s[18:19], 0, v[160:161]
	v_lshl_add_u64 v[156:157], s[12:13], 0, v[160:161]
	v_mad_i64_i32 v[160:161], s[38:39], s49, v211, v[164:165]
	global_load_dwordx4 v[156:159], v[156:157], off
	s_add_i32 s50, s49, 8
	s_add_i32 s48, s49, 16
	s_add_i32 s47, s49, 24
	s_add_i32 s81, s49, 32
	s_add_i32 s80, s49, 40
	s_add_i32 s79, s49, 48
	s_add_i32 s78, s49, 56
	s_lshl_b32 s77, s46, 8
	global_load_dwordx4 v[160:163], v[160:161], off
	v_mad_i64_i32 v[212:213], s[38:39], s50, v211, v[164:165]
	global_load_dwordx4 v[212:215], v[212:213], off
	v_mad_i64_i32 v[216:217], s[38:39], s48, v211, v[164:165]
	global_load_dwordx4 v[216:219], v[216:217], off
	v_mad_i64_i32 v[220:221], s[38:39], s47, v211, v[164:165]
	global_load_dwordx4 v[220:223], v[220:221], off
	v_mad_i64_i32 v[230:231], s[38:39], s81, v211, v[164:165]
	global_load_dwordx4 v[230:233], v[230:231], off
	v_mad_i64_i32 v[234:235], s[38:39], s80, v211, v[164:165]
	global_load_dwordx4 v[234:237], v[234:235], off
	v_mad_i64_i32 v[238:239], s[38:39], s79, v211, v[164:165]
	global_load_dwordx4 v[238:241], v[238:239], off
	v_mad_i64_i32 v[246:247], s[38:39], s78, v211, v[164:165]
	global_load_dwordx4 v[246:249], v[246:247], off
	v_ashrrev_i32_e32 v169, 31, v168
	v_readfirstlane_b32 s82, v180
	s_waitcnt vmcnt(7)
	v_pk_add_f32 v[160:161], v[156:157], v[160:161]
	v_pk_add_f32 v[162:163], v[158:159], v[162:163]
	s_waitcnt vmcnt(6)
	v_pk_add_f32 v[160:161], v[160:161], v[212:213]
	v_pk_add_f32 v[162:163], v[162:163], v[214:215]
	s_waitcnt vmcnt(5)
	v_pk_add_f32 v[160:161], v[160:161], v[216:217]
	v_pk_add_f32 v[162:163], v[162:163], v[218:219]
	s_waitcnt vmcnt(4)
	v_pk_add_f32 v[160:161], v[160:161], v[220:221]
	v_pk_add_f32 v[162:163], v[162:163], v[222:223]
	s_waitcnt vmcnt(3)
	v_pk_add_f32 v[160:161], v[160:161], v[230:231]
	v_pk_add_f32 v[162:163], v[162:163], v[232:233]
	s_waitcnt vmcnt(2)
	v_pk_add_f32 v[160:161], v[160:161], v[234:235]
	v_pk_add_f32 v[162:163], v[162:163], v[236:237]
	s_waitcnt vmcnt(1)
	v_pk_add_f32 v[160:161], v[160:161], v[238:239]
	v_pk_add_f32 v[162:163], v[162:163], v[240:241]
	s_waitcnt vmcnt(0)
	v_pk_add_f32 v[158:159], v[162:163], v[248:249]
	v_pk_add_f32 v[160:161], v[160:161], v[246:247]
	v_pk_mul_f32 v[156:157], v[158:159], 0.5 op_sel_hi:[1, 0]
	v_pk_mul_f32 v[158:159], v[160:161], 0.5 op_sel_hi:[1, 0]
	v_add_u32_e32 v160, 0x810, v168
	v_ashrrev_i32_e32 v161, 31, v160
	v_lshlrev_b64 v[164:165], 2, v[160:161]
	v_lshl_add_u64 v[170:171], s[18:19], 0, v[164:165]
	v_lshl_add_u64 v[160:161], s[12:13], 0, v[164:165]
	v_mad_i64_i32 v[164:165], s[38:39], s49, v211, v[170:171]
	global_load_dwordx4 v[160:163], v[160:161], off
	global_load_dwordx4 v[164:167], v[164:165], off
	v_mad_i64_i32 v[212:213], s[38:39], s50, v211, v[170:171]
	global_load_dwordx4 v[212:215], v[212:213], off
	v_mad_i64_i32 v[216:217], s[38:39], s48, v211, v[170:171]
	global_load_dwordx4 v[216:219], v[216:217], off
	v_mad_i64_i32 v[220:221], s[38:39], s47, v211, v[170:171]
	global_load_dwordx4 v[220:223], v[220:221], off
	v_mad_i64_i32 v[230:231], s[38:39], s81, v211, v[170:171]
	global_load_dwordx4 v[230:233], v[230:231], off
	v_mad_i64_i32 v[234:235], s[38:39], s80, v211, v[170:171]
	global_load_dwordx4 v[234:237], v[234:235], off
	v_mad_i64_i32 v[238:239], s[38:39], s79, v211, v[170:171]
	global_load_dwordx4 v[238:241], v[238:239], off
	v_mad_i64_i32 v[246:247], s[38:39], s78, v211, v[170:171]
	global_load_dwordx4 v[246:249], v[246:247], off
	s_waitcnt vmcnt(7)
	v_pk_add_f32 v[164:165], v[160:161], v[164:165]
	v_pk_add_f32 v[166:167], v[162:163], v[166:167]
	s_waitcnt vmcnt(6)
	v_pk_add_f32 v[164:165], v[164:165], v[212:213]
	v_pk_add_f32 v[166:167], v[166:167], v[214:215]
	s_waitcnt vmcnt(5)
	v_pk_add_f32 v[164:165], v[164:165], v[216:217]
	v_pk_add_f32 v[166:167], v[166:167], v[218:219]
	s_waitcnt vmcnt(4)
	v_pk_add_f32 v[164:165], v[164:165], v[220:221]
	v_pk_add_f32 v[166:167], v[166:167], v[222:223]
	s_waitcnt vmcnt(3)
	v_pk_add_f32 v[164:165], v[164:165], v[230:231]
	v_pk_add_f32 v[166:167], v[166:167], v[232:233]
	s_waitcnt vmcnt(2)
	v_pk_add_f32 v[164:165], v[164:165], v[234:235]
	v_pk_add_f32 v[166:167], v[166:167], v[236:237]
	s_waitcnt vmcnt(1)
	v_pk_add_f32 v[164:165], v[164:165], v[238:239]
	v_pk_add_f32 v[166:167], v[166:167], v[240:241]
	s_waitcnt vmcnt(0)
	v_pk_add_f32 v[162:163], v[166:167], v[248:249]
	v_pk_add_f32 v[164:165], v[164:165], v[246:247]
	v_pk_mul_f32 v[160:161], v[162:163], 0.5 op_sel_hi:[1, 0]
	v_pk_mul_f32 v[162:163], v[164:165], 0.5 op_sel_hi:[1, 0]
	v_add_u32_e32 v164, 0x880, v168
	v_ashrrev_i32_e32 v165, 31, v164
	v_lshlrev_b64 v[170:171], 2, v[164:165]
	v_lshl_add_u64 v[174:175], s[18:19], 0, v[170:171]
	v_lshl_add_u64 v[164:165], s[12:13], 0, v[170:171]
	v_mad_i64_i32 v[170:171], s[38:39], s49, v211, v[174:175]
	global_load_dwordx4 v[164:167], v[164:165], off
	global_load_dwordx4 v[170:173], v[170:171], off
	v_mad_i64_i32 v[212:213], s[38:39], s50, v211, v[174:175]
	global_load_dwordx4 v[212:215], v[212:213], off
	v_mad_i64_i32 v[216:217], s[38:39], s48, v211, v[174:175]
	global_load_dwordx4 v[216:219], v[216:217], off
	v_mad_i64_i32 v[220:221], s[38:39], s47, v211, v[174:175]
	global_load_dwordx4 v[220:223], v[220:221], off
	v_mad_i64_i32 v[230:231], s[38:39], s81, v211, v[174:175]
	global_load_dwordx4 v[230:233], v[230:231], off
	v_mad_i64_i32 v[234:235], s[38:39], s80, v211, v[174:175]
	global_load_dwordx4 v[234:237], v[234:235], off
	v_mad_i64_i32 v[238:239], s[38:39], s79, v211, v[174:175]
	global_load_dwordx4 v[238:241], v[238:239], off
	v_mad_i64_i32 v[246:247], s[38:39], s78, v211, v[174:175]
	global_load_dwordx4 v[246:249], v[246:247], off
	s_waitcnt vmcnt(7)
	v_pk_add_f32 v[170:171], v[164:165], v[170:171]
	v_pk_add_f32 v[172:173], v[166:167], v[172:173]
	s_waitcnt vmcnt(6)
	v_pk_add_f32 v[170:171], v[170:171], v[212:213]
	v_pk_add_f32 v[172:173], v[172:173], v[214:215]
	s_waitcnt vmcnt(5)
	v_pk_add_f32 v[170:171], v[170:171], v[216:217]
	v_pk_add_f32 v[172:173], v[172:173], v[218:219]
	s_waitcnt vmcnt(4)
	v_pk_add_f32 v[170:171], v[170:171], v[220:221]
	v_pk_add_f32 v[172:173], v[172:173], v[222:223]
	s_waitcnt vmcnt(3)
	v_pk_add_f32 v[170:171], v[170:171], v[230:231]
	v_pk_add_f32 v[172:173], v[172:173], v[232:233]
	s_waitcnt vmcnt(2)
	v_pk_add_f32 v[170:171], v[170:171], v[234:235]
	v_pk_add_f32 v[172:173], v[172:173], v[236:237]
	s_waitcnt vmcnt(1)
	v_pk_add_f32 v[170:171], v[170:171], v[238:239]
	v_pk_add_f32 v[172:173], v[172:173], v[240:241]
	s_waitcnt vmcnt(0)
	v_pk_add_f32 v[166:167], v[172:173], v[248:249]
	v_pk_add_f32 v[170:171], v[170:171], v[246:247]
	v_pk_mul_f32 v[164:165], v[166:167], 0.5 op_sel_hi:[1, 0]
	v_pk_mul_f32 v[166:167], v[170:171], 0.5 op_sel_hi:[1, 0]
	v_add_u32_e32 v170, 0x890, v168
	v_ashrrev_i32_e32 v171, 31, v170
	v_lshlrev_b64 v[174:175], 2, v[170:171]
	v_lshl_add_u64 v[178:179], s[18:19], 0, v[174:175]
	v_lshl_add_u64 v[170:171], s[12:13], 0, v[174:175]
	v_mad_i64_i32 v[174:175], s[38:39], s49, v211, v[178:179]
	global_load_dwordx4 v[170:173], v[170:171], off
	global_load_dwordx4 v[174:177], v[174:175], off
	v_mad_i64_i32 v[212:213], s[38:39], s50, v211, v[178:179]
	global_load_dwordx4 v[212:215], v[212:213], off
	v_mad_i64_i32 v[216:217], s[38:39], s48, v211, v[178:179]
	global_load_dwordx4 v[216:219], v[216:217], off
	v_mad_i64_i32 v[220:221], s[38:39], s47, v211, v[178:179]
	global_load_dwordx4 v[220:223], v[220:221], off
	v_mad_i64_i32 v[230:231], s[38:39], s81, v211, v[178:179]
	global_load_dwordx4 v[230:233], v[230:231], off
	v_mad_i64_i32 v[234:235], s[38:39], s80, v211, v[178:179]
	global_load_dwordx4 v[234:237], v[234:235], off
	v_mad_i64_i32 v[238:239], s[38:39], s79, v211, v[178:179]
	global_load_dwordx4 v[238:241], v[238:239], off
	v_mad_i64_i32 v[246:247], s[38:39], s78, v211, v[178:179]
	global_load_dwordx4 v[246:249], v[246:247], off
	v_lshlrev_b64 v[168:169], 2, v[168:169]
	s_waitcnt vmcnt(7)
	v_pk_add_f32 v[174:175], v[170:171], v[174:175]
	v_pk_add_f32 v[176:177], v[172:173], v[176:177]
	s_waitcnt vmcnt(6)
	v_pk_add_f32 v[174:175], v[174:175], v[212:213]
	v_pk_add_f32 v[176:177], v[176:177], v[214:215]
	s_waitcnt vmcnt(5)
	v_pk_add_f32 v[174:175], v[174:175], v[216:217]
	v_pk_add_f32 v[176:177], v[176:177], v[218:219]
	s_waitcnt vmcnt(4)
	v_pk_add_f32 v[174:175], v[174:175], v[220:221]
	v_pk_add_f32 v[176:177], v[176:177], v[222:223]
	s_waitcnt vmcnt(3)
	v_pk_add_f32 v[174:175], v[174:175], v[230:231]
	v_pk_add_f32 v[176:177], v[176:177], v[232:233]
	s_waitcnt vmcnt(2)
	v_pk_add_f32 v[174:175], v[174:175], v[234:235]
	v_pk_add_f32 v[176:177], v[176:177], v[236:237]
	s_waitcnt vmcnt(1)
	v_pk_add_f32 v[174:175], v[174:175], v[238:239]
	v_pk_add_f32 v[176:177], v[176:177], v[240:241]
	v_add_u32_e32 v178, s77, v181
	v_ashrrev_i32_e32 v179, 31, v178
	v_or_b32_e32 v228, 16, v178
	v_ashrrev_i32_e32 v229, 31, v228
	v_lshlrev_b64 v[244:245], 12, v[228:229]
	s_waitcnt vmcnt(0)
	v_pk_add_f32 v[172:173], v[176:177], v[248:249]
	v_pk_add_f32 v[174:175], v[174:175], v[246:247]
	v_pk_mul_f32 v[170:171], v[172:173], 0.5 op_sel_hi:[1, 0]
	v_pk_mul_f32 v[172:173], v[174:175], 0.5 op_sel_hi:[1, 0]
	v_lshl_add_u64 v[174:175], s[2:3], 0, v[168:169]
	v_lshlrev_b64 v[176:177], 12, v[178:179]
	v_lshl_add_u64 v[224:225], v[174:175], 0, v[176:177]
	global_load_dwordx4 v[212:215], v[224:225], off
	global_load_dwordx4 v[216:219], v[224:225], off offset:64
	global_load_dwordx4 v[220:223], v[224:225], off offset:512
	s_nop 0
	global_load_dwordx4 v[224:227], v[224:225], off offset:576
	v_lshl_add_u64 v[240:241], v[174:175], 0, v[244:245]
	global_load_dwordx4 v[228:231], v[240:241], off
	global_load_dwordx4 v[232:235], v[240:241], off offset:64
	global_load_dwordx4 v[236:239], v[240:241], off offset:512
	s_nop 0
	global_load_dwordx4 v[240:243], v[240:241], off offset:576
	s_waitcnt vmcnt(7)
	v_pk_fma_f32 v[124:125], v[124:125], v[158:159], v[212:213]
	v_lshl_add_u64 v[212:213], s[16:17], 0, v[176:177]
	v_lshl_add_u64 v[212:213], v[212:213], 0, v[168:169]
	s_waitcnt vmcnt(5)
	v_pk_fma_f32 v[114:115], v[114:115], v[164:165], v[222:223]
	v_pk_fma_f32 v[112:113], v[112:113], v[166:167], v[220:221]
	global_store_dwordx4 v[212:213], v[112:115], off offset:512
	s_waitcnt vmcnt(5)
	v_pk_fma_f32 v[106:107], v[106:107], v[170:171], v[226:227]
	v_pk_fma_f32 v[104:105], v[104:105], v[172:173], v[224:225]
	v_lshl_add_u64 v[112:113], s[16:17], 0, v[244:245]
	v_lshl_add_u64 v[112:113], v[112:113], 0, v[168:169]
	s_waitcnt vmcnt(1)
	v_pk_fma_f32 v[98:99], v[98:99], v[170:171], v[242:243]
	v_pk_fma_f32 v[96:97], v[96:97], v[172:173], v[240:241]
	global_store_dwordx4 v[212:213], v[104:107], off offset:576
	global_store_dwordx4 v[112:113], v[96:99], off offset:576
	v_pk_fma_f32 v[126:127], v[126:127], v[156:157], v[214:215]
	v_pk_fma_f32 v[106:107], v[118:119], v[156:157], v[230:231]
	v_pk_fma_f32 v[104:105], v[116:117], v[158:159], v[228:229]
	v_or_b32_e32 v96, 32, v178
	v_pk_fma_f32 v[122:123], v[122:123], v[160:161], v[218:219]
	v_pk_fma_f32 v[120:121], v[120:121], v[162:163], v[216:217]
	global_store_dwordx4 v[112:113], v[104:107], off
	v_pk_fma_f32 v[102:103], v[102:103], v[164:165], v[238:239]
	v_pk_fma_f32 v[100:101], v[100:101], v[166:167], v[236:237]
	v_pk_fma_f32 v[106:107], v[110:111], v[160:161], v[234:235]
	v_pk_fma_f32 v[104:105], v[108:109], v[162:163], v[232:233]
	v_ashrrev_i32_e32 v97, 31, v96
	global_store_dwordx4 v[212:213], v[124:127], off
	global_store_dwordx4 v[212:213], v[120:123], off offset:64
	global_store_dwordx4 v[112:113], v[104:107], off offset:64
	global_store_dwordx4 v[112:113], v[100:103], off offset:512
	v_lshlrev_b64 v[212:213], 12, v[96:97]
	v_or_b32_e32 v112, 48, v178
	v_lshl_add_u64 v[108:109], v[174:175], 0, v[212:213]
	v_ashrrev_i32_e32 v113, 31, v112
	global_load_dwordx4 v[96:99], v[108:109], off
	global_load_dwordx4 v[100:103], v[108:109], off offset:64
	global_load_dwordx4 v[104:107], v[108:109], off offset:512
	s_nop 0
	global_load_dwordx4 v[108:111], v[108:109], off offset:576
	v_lshlrev_b64 v[178:179], 12, v[112:113]
	v_lshl_add_u64 v[124:125], v[174:175], 0, v[178:179]
	global_load_dwordx4 v[112:115], v[124:125], off
	global_load_dwordx4 v[116:119], v[124:125], off offset:64
	global_load_dwordx4 v[120:123], v[124:125], off offset:512
	s_nop 0
	global_load_dwordx4 v[124:127], v[124:125], off offset:576
	s_waitcnt vmcnt(7)
	v_pk_fma_f32 v[92:93], v[92:93], v[158:159], v[96:97]
	v_lshl_add_u64 v[96:97], s[16:17], 0, v[212:213]
	v_lshl_add_u64 v[96:97], v[96:97], 0, v[168:169]
	s_waitcnt vmcnt(5)
	v_pk_fma_f32 v[82:83], v[82:83], v[164:165], v[106:107]
	v_pk_fma_f32 v[80:81], v[80:81], v[166:167], v[104:105]
	global_store_dwordx4 v[96:97], v[80:83], off offset:512
	s_waitcnt vmcnt(5)
	v_pk_fma_f32 v[74:75], v[74:75], v[170:171], v[110:111]
	v_pk_fma_f32 v[72:73], v[72:73], v[172:173], v[108:109]
	v_lshl_add_u64 v[80:81], s[16:17], 0, v[178:179]
	v_pk_fma_f32 v[94:95], v[94:95], v[156:157], v[98:99]
	v_pk_fma_f32 v[90:91], v[90:91], v[160:161], v[102:103]
	v_pk_fma_f32 v[88:89], v[88:89], v[162:163], v[100:101]
	global_store_dwordx4 v[96:97], v[72:75], off offset:576
	v_lshl_add_u64 v[80:81], v[80:81], 0, v[168:169]
	global_store_dwordx4 v[96:97], v[92:95], off
	s_waitcnt vmcnt(6)
	v_pk_fma_f32 v[74:75], v[86:87], v[156:157], v[114:115]
	v_pk_fma_f32 v[72:73], v[84:85], v[158:159], v[112:113]
	global_store_dwordx4 v[96:97], v[88:91], off offset:64
	global_store_dwordx4 v[80:81], v[72:75], off
	s_waitcnt vmcnt(6)
	v_pk_fma_f32 v[70:71], v[70:71], v[164:165], v[122:123]
	v_pk_fma_f32 v[68:69], v[68:69], v[166:167], v[120:121]
	v_pk_fma_f32 v[74:75], v[78:79], v[160:161], v[118:119]
	v_pk_fma_f32 v[72:73], v[76:77], v[162:163], v[116:117]
	s_waitcnt vmcnt(5)
	v_pk_fma_f32 v[66:67], v[66:67], v[170:171], v[126:127]
	v_pk_fma_f32 v[64:65], v[64:65], v[172:173], v[124:125]
	v_lshl_add_u64 v[96:97], v[176:177], 0, s[22:23]
	global_store_dwordx4 v[80:81], v[72:75], off offset:64
	global_store_dwordx4 v[80:81], v[68:71], off offset:512
	global_store_dwordx4 v[80:81], v[64:67], off offset:576
	v_lshl_add_u64 v[76:77], v[174:175], 0, v[96:97]
	global_load_dwordx4 v[64:67], v[76:77], off
	global_load_dwordx4 v[68:71], v[76:77], off offset:64
	global_load_dwordx4 v[72:75], v[76:77], off offset:512
	s_nop 0
	global_load_dwordx4 v[76:79], v[76:77], off offset:576
	v_lshl_add_u64 v[98:99], v[176:177], 0, s[24:25]
	v_lshl_add_u64 v[92:93], v[174:175], 0, v[98:99]
	global_load_dwordx4 v[80:83], v[92:93], off
	global_load_dwordx4 v[84:87], v[92:93], off offset:64
	global_load_dwordx4 v[88:91], v[92:93], off offset:512
	s_nop 0
	global_load_dwordx4 v[92:95], v[92:93], off offset:576
	s_waitcnt vmcnt(7)
	v_pk_fma_f32 v[60:61], v[60:61], v[158:159], v[64:65]
	v_lshl_add_u64 v[64:65], s[16:17], 0, v[96:97]
	v_lshl_add_u64 v[64:65], v[64:65], 0, v[168:169]
	s_waitcnt vmcnt(5)
	v_pk_fma_f32 v[50:51], v[50:51], v[164:165], v[74:75]
	v_pk_fma_f32 v[48:49], v[48:49], v[166:167], v[72:73]
	global_store_dwordx4 v[64:65], v[48:51], off offset:512
	s_waitcnt vmcnt(5)
	v_pk_fma_f32 v[42:43], v[42:43], v[170:171], v[78:79]
	v_pk_fma_f32 v[40:41], v[40:41], v[172:173], v[76:77]
	v_lshl_add_u64 v[48:49], s[16:17], 0, v[98:99]
	v_pk_fma_f32 v[62:63], v[62:63], v[156:157], v[66:67]
	v_pk_fma_f32 v[58:59], v[58:59], v[160:161], v[70:71]
	v_pk_fma_f32 v[56:57], v[56:57], v[162:163], v[68:69]
	global_store_dwordx4 v[64:65], v[40:43], off offset:576
	v_lshl_add_u64 v[48:49], v[48:49], 0, v[168:169]
	global_store_dwordx4 v[64:65], v[60:63], off
	s_waitcnt vmcnt(6)
	v_pk_fma_f32 v[42:43], v[54:55], v[156:157], v[82:83]
	v_pk_fma_f32 v[40:41], v[52:53], v[158:159], v[80:81]
	global_store_dwordx4 v[64:65], v[56:59], off offset:64
	global_store_dwordx4 v[48:49], v[40:43], off
	s_waitcnt vmcnt(6)
	v_pk_fma_f32 v[38:39], v[38:39], v[164:165], v[90:91]
	v_pk_fma_f32 v[36:37], v[36:37], v[166:167], v[88:89]
	v_pk_fma_f32 v[42:43], v[46:47], v[160:161], v[86:87]
	v_pk_fma_f32 v[40:41], v[44:45], v[162:163], v[84:85]
	s_waitcnt vmcnt(5)
	v_pk_fma_f32 v[30:31], v[30:31], v[170:171], v[94:95]
	v_pk_fma_f32 v[28:29], v[28:29], v[172:173], v[92:93]
	v_lshl_add_u64 v[64:65], v[176:177], 0, s[26:27]
	global_store_dwordx4 v[48:49], v[40:43], off offset:64
	global_store_dwordx4 v[48:49], v[36:39], off offset:512
	global_store_dwordx4 v[48:49], v[28:31], off offset:576
	v_lshl_add_u64 v[44:45], v[174:175], 0, v[64:65]
	global_load_dwordx4 v[28:31], v[44:45], off
	global_load_dwordx4 v[36:39], v[44:45], off offset:64
	global_load_dwordx4 v[40:43], v[44:45], off offset:512
	s_nop 0
	global_load_dwordx4 v[44:47], v[44:45], off offset:576
	v_lshl_add_u64 v[66:67], v[176:177], 0, s[28:29]
	v_lshl_add_u64 v[60:61], v[174:175], 0, v[66:67]
	global_load_dwordx4 v[48:51], v[60:61], off
	global_load_dwordx4 v[52:55], v[60:61], off offset:64
	global_load_dwordx4 v[56:59], v[60:61], off offset:512
	s_nop 0
	global_load_dwordx4 v[60:63], v[60:61], off offset:576
	s_waitcnt vmcnt(7)
	v_pk_fma_f32 v[28:29], v[32:33], v[158:159], v[28:29]
	v_lshl_add_u64 v[32:33], s[16:17], 0, v[64:65]
	v_lshl_add_u64 v[32:33], v[32:33], 0, v[168:169]
	s_waitcnt vmcnt(5)
	v_pk_fma_f32 v[18:19], v[18:19], v[164:165], v[42:43]
	v_pk_fma_f32 v[16:17], v[16:17], v[166:167], v[40:41]
	global_store_dwordx4 v[32:33], v[16:19], off offset:512
	s_waitcnt vmcnt(5)
	v_pk_fma_f32 v[10:11], v[10:11], v[170:171], v[46:47]
	v_pk_fma_f32 v[8:9], v[8:9], v[172:173], v[44:45]
	v_lshl_add_u64 v[16:17], s[16:17], 0, v[66:67]
	global_store_dwordx4 v[32:33], v[8:11], off offset:576
	v_lshl_add_u64 v[16:17], v[16:17], 0, v[168:169]
	v_pk_fma_f32 v[30:31], v[34:35], v[156:157], v[30:31]
	s_waitcnt vmcnt(5)
	v_pk_fma_f32 v[10:11], v[22:23], v[156:157], v[50:51]
	v_pk_fma_f32 v[8:9], v[20:21], v[158:159], v[48:49]
	v_pk_fma_f32 v[26:27], v[26:27], v[160:161], v[38:39]
	v_pk_fma_f32 v[24:25], v[24:25], v[162:163], v[36:37]
	global_store_dwordx4 v[16:17], v[8:11], off
	s_waitcnt vmcnt(4)
	v_pk_fma_f32 v[6:7], v[6:7], v[164:165], v[58:59]
	v_pk_fma_f32 v[4:5], v[4:5], v[166:167], v[56:57]
	v_pk_fma_f32 v[10:11], v[14:15], v[160:161], v[54:55]
	v_pk_fma_f32 v[8:9], v[12:13], v[162:163], v[52:53]
	s_waitcnt vmcnt(3)
	v_pk_fma_f32 v[2:3], v[2:3], v[170:171], v[62:63]
	v_pk_fma_f32 v[0:1], v[0:1], v[172:173], v[60:61]
	global_store_dwordx4 v[32:33], v[28:31], off
	global_store_dwordx4 v[32:33], v[24:27], off offset:64
	global_store_dwordx4 v[16:17], v[8:11], off offset:64
	global_store_dwordx4 v[16:17], v[4:7], off offset:512
	global_store_dwordx4 v[16:17], v[0:3], off offset:576
	s_waitcnt vmcnt(0)
	s_barrier
	s_and_saveexec_b64 s[38:39], s[4:5]
	s_cbranch_execz .LBB0_425
	s_lshl_b32 s40, s46, 2
	s_ashr_i32 s41, s40, 31
	s_lshl_b64 s[40:41], s[40:41], 2
	s_add_u32 s40, s65, s40
	s_addc_u32 s41, s66, s41
	s_getreg_b32 s42, hwreg(HW_REG_XCC_ID, 0, 4)
	global_load_dwordx4 v[0:3], v129, s[40:41]
	s_and_b32 s40, s42, 15
	s_add_i32 s40, s40, 1
	s_waitcnt vmcnt(0)
	v_cmp_ne_u32_e32 vcc, s40, v2
	s_nop 1
	v_cndmask_b32_e64 v2, 0, 1, vcc
	v_cmp_ne_u32_e32 vcc, s40, v3
	v_lshlrev_b32_e32 v2, 2, v2
	s_nop 0
	v_cndmask_b32_e64 v3, 0, 1, vcc
	v_cmp_ne_u32_e32 vcc, s40, v1
	v_lshlrev_b32_e32 v3, 3, v3
	v_or_b32_e32 v2, v3, v2
	v_cndmask_b32_e64 v1, 0, 1, vcc
	v_cmp_ne_u32_e32 vcc, s40, v0
	v_lshlrev_b32_e32 v1, 1, v1
	s_nop 0
	v_cndmask_b32_e64 v0, 0, 1, vcc
	v_or_b32_e32 v0, v0, v1
	v_and_b32_e32 v0, 3, v0
	v_or_b32_e32 v0, v0, v2
	v_and_b32_e32 v0, 15, v0
	v_cmp_eq_u32_e32 vcc, 0, v0
	s_cbranch_vccnz .LBB0_414
	buffer_wbl2 sc1
	s_waitcnt vmcnt(0)

.LBB0_1174:
	v_lshl_or_b32 v172, s42, 8, v198
	v_add_u32_e32 v156, 0x1400, v172
	v_ashrrev_i32_e32 v157, 31, v156
	v_lshlrev_b64 v[160:161], 2, v[156:157]
	s_ashr_i32 s54, s44, 3
	v_lshl_add_u64 v[164:165], s[2:3], 0, v[160:161]
	v_lshl_add_u64 v[156:157], s[12:13], 0, v[160:161]
	v_mad_i64_i32 v[160:161], s[46:47], s54, v211, v[164:165]
	global_load_dwordx4 v[156:159], v[156:157], off
	s_add_i32 s55, s54, 8
	s_add_i32 s53, s54, 16
	s_add_i32 s52, s54, 24
	s_add_i32 s81, s54, 32
	s_add_i32 s80, s54, 40
	s_add_i32 s43, s54, 48
	s_add_i32 s37, s54, 56
	s_lshl_b32 s35, s44, 8
	global_load_dwordx4 v[160:163], v[160:161], off
	v_mad_i64_i32 v[212:213], s[46:47], s55, v211, v[164:165]
	global_load_dwordx4 v[212:215], v[212:213], off
	v_mad_i64_i32 v[216:217], s[46:47], s53, v211, v[164:165]
	global_load_dwordx4 v[216:219], v[216:217], off
	v_mad_i64_i32 v[220:221], s[46:47], s52, v211, v[164:165]
	global_load_dwordx4 v[220:223], v[220:221], off
	v_mad_i64_i32 v[224:225], s[46:47], s81, v211, v[164:165]
	global_load_dwordx4 v[224:227], v[224:225], off
	v_mad_i64_i32 v[228:229], s[46:47], s80, v211, v[164:165]
	global_load_dwordx4 v[228:231], v[228:229], off
	v_mad_i64_i32 v[232:233], s[46:47], s43, v211, v[164:165]
	global_load_dwordx4 v[232:235], v[232:233], off
	v_mad_i64_i32 v[236:237], s[46:47], s37, v211, v[164:165]
	global_load_dwordx4 v[236:239], v[236:237], off
	v_ashrrev_i32_e32 v173, 31, v172
	v_readfirstlane_b32 s82, v180
	s_waitcnt vmcnt(7)
	v_pk_add_f32 v[160:161], v[156:157], v[160:161]
	v_pk_add_f32 v[162:163], v[158:159], v[162:163]
	s_waitcnt vmcnt(6)
	v_pk_add_f32 v[160:161], v[160:161], v[212:213]
	v_pk_add_f32 v[162:163], v[162:163], v[214:215]
	s_waitcnt vmcnt(5)
	v_pk_add_f32 v[160:161], v[160:161], v[216:217]
	v_pk_add_f32 v[162:163], v[162:163], v[218:219]
	s_waitcnt vmcnt(4)
	v_pk_add_f32 v[160:161], v[160:161], v[220:221]
	v_pk_add_f32 v[162:163], v[162:163], v[222:223]
	s_waitcnt vmcnt(3)
	v_pk_add_f32 v[160:161], v[160:161], v[224:225]
	v_pk_add_f32 v[162:163], v[162:163], v[226:227]
	s_waitcnt vmcnt(2)
	v_pk_add_f32 v[160:161], v[160:161], v[228:229]
	v_pk_add_f32 v[162:163], v[162:163], v[230:231]
	s_waitcnt vmcnt(1)
	v_pk_add_f32 v[166:167], v[160:161], v[232:233]
	v_pk_add_f32 v[162:163], v[162:163], v[234:235]
	s_waitcnt vmcnt(0)
	v_pk_add_f32 v[156:157], v[162:163], v[238:239]
	v_add_u32_e32 v160, 0x1410, v172
	v_ashrrev_i32_e32 v161, 31, v160
	v_lshlrev_b64 v[164:165], 2, v[160:161]
	v_lshl_add_u64 v[168:169], s[2:3], 0, v[164:165]
	v_lshl_add_u64 v[160:161], s[12:13], 0, v[164:165]
	v_mad_i64_i32 v[164:165], s[46:47], s54, v211, v[168:169]
	v_pk_add_f32 v[158:159], v[166:167], v[236:237]
	global_load_dwordx4 v[160:163], v[160:161], off
	global_load_dwordx4 v[164:167], v[164:165], off
	v_mad_i64_i32 v[212:213], s[46:47], s55, v211, v[168:169]
	global_load_dwordx4 v[212:215], v[212:213], off
	v_mad_i64_i32 v[216:217], s[46:47], s53, v211, v[168:169]
	global_load_dwordx4 v[216:219], v[216:217], off
	v_mad_i64_i32 v[220:221], s[46:47], s52, v211, v[168:169]
	global_load_dwordx4 v[220:223], v[220:221], off
	v_mad_i64_i32 v[224:225], s[46:47], s81, v211, v[168:169]
	global_load_dwordx4 v[224:227], v[224:225], off
	v_mad_i64_i32 v[228:229], s[46:47], s80, v211, v[168:169]
	global_load_dwordx4 v[228:231], v[228:229], off
	v_mad_i64_i32 v[232:233], s[46:47], s43, v211, v[168:169]
	global_load_dwordx4 v[232:235], v[232:233], off
	v_mad_i64_i32 v[236:237], s[46:47], s37, v211, v[168:169]
	global_load_dwordx4 v[236:239], v[236:237], off
	s_waitcnt vmcnt(7)
	v_pk_add_f32 v[164:165], v[160:161], v[164:165]
	v_pk_add_f32 v[166:167], v[162:163], v[166:167]
	s_waitcnt vmcnt(6)
	v_pk_add_f32 v[164:165], v[164:165], v[212:213]
	v_pk_add_f32 v[166:167], v[166:167], v[214:215]
	s_waitcnt vmcnt(5)
	v_pk_add_f32 v[164:165], v[164:165], v[216:217]
	v_pk_add_f32 v[166:167], v[166:167], v[218:219]
	s_waitcnt vmcnt(4)
	v_pk_add_f32 v[164:165], v[164:165], v[220:221]
	v_pk_add_f32 v[166:167], v[166:167], v[222:223]
	s_waitcnt vmcnt(3)
	v_pk_add_f32 v[164:165], v[164:165], v[224:225]
	v_pk_add_f32 v[166:167], v[166:167], v[226:227]
	s_waitcnt vmcnt(2)
	v_pk_add_f32 v[164:165], v[164:165], v[228:229]
	v_pk_add_f32 v[166:167], v[166:167], v[230:231]
	s_waitcnt vmcnt(1)
	v_pk_add_f32 v[170:171], v[164:165], v[232:233]
	v_pk_add_f32 v[166:167], v[166:167], v[234:235]
	s_waitcnt vmcnt(0)
	v_pk_add_f32 v[160:161], v[166:167], v[238:239]
	v_add_u32_e32 v164, 0x1480, v172
	v_ashrrev_i32_e32 v165, 31, v164
	v_lshlrev_b64 v[168:169], 2, v[164:165]
	v_lshl_add_u64 v[174:175], s[2:3], 0, v[168:169]
	v_lshl_add_u64 v[164:165], s[12:13], 0, v[168:169]
	v_mad_i64_i32 v[168:169], s[46:47], s54, v211, v[174:175]
	v_pk_add_f32 v[162:163], v[170:171], v[236:237]
	global_load_dwordx4 v[164:167], v[164:165], off
	global_load_dwordx4 v[168:171], v[168:169], off
	v_mad_i64_i32 v[212:213], s[46:47], s55, v211, v[174:175]
	global_load_dwordx4 v[212:215], v[212:213], off
	v_mad_i64_i32 v[216:217], s[46:47], s53, v211, v[174:175]
	global_load_dwordx4 v[216:219], v[216:217], off
	v_mad_i64_i32 v[220:221], s[46:47], s52, v211, v[174:175]
	global_load_dwordx4 v[220:223], v[220:221], off
	v_mad_i64_i32 v[224:225], s[46:47], s81, v211, v[174:175]
	global_load_dwordx4 v[224:227], v[224:225], off
	v_mad_i64_i32 v[228:229], s[46:47], s80, v211, v[174:175]
	global_load_dwordx4 v[228:231], v[228:229], off
	v_mad_i64_i32 v[232:233], s[46:47], s43, v211, v[174:175]
	global_load_dwordx4 v[232:235], v[232:233], off
	v_mad_i64_i32 v[236:237], s[46:47], s37, v211, v[174:175]
	global_load_dwordx4 v[236:239], v[236:237], off
	s_waitcnt vmcnt(7)
	v_pk_add_f32 v[168:169], v[164:165], v[168:169]
	v_pk_add_f32 v[170:171], v[166:167], v[170:171]
	s_waitcnt vmcnt(6)
	v_pk_add_f32 v[168:169], v[168:169], v[212:213]
	v_pk_add_f32 v[170:171], v[170:171], v[214:215]
	s_waitcnt vmcnt(5)
	v_pk_add_f32 v[168:169], v[168:169], v[216:217]
	v_pk_add_f32 v[170:171], v[170:171], v[218:219]
	s_waitcnt vmcnt(4)
	v_pk_add_f32 v[168:169], v[168:169], v[220:221]
	v_pk_add_f32 v[170:171], v[170:171], v[222:223]
	s_waitcnt vmcnt(3)
	v_pk_add_f32 v[168:169], v[168:169], v[224:225]
	v_pk_add_f32 v[170:171], v[170:171], v[226:227]
	s_waitcnt vmcnt(2)
	v_pk_add_f32 v[168:169], v[168:169], v[228:229]
	v_pk_add_f32 v[170:171], v[170:171], v[230:231]
	s_waitcnt vmcnt(1)
	v_pk_add_f32 v[176:177], v[168:169], v[232:233]
	v_pk_add_f32 v[170:171], v[170:171], v[234:235]
	s_waitcnt vmcnt(0)
	v_pk_add_f32 v[164:165], v[170:171], v[238:239]
	v_add_u32_e32 v168, 0x1490, v172
	v_ashrrev_i32_e32 v169, 31, v168
	v_lshlrev_b64 v[174:175], 2, v[168:169]
	v_lshl_add_u64 v[178:179], s[2:3], 0, v[174:175]
	v_lshl_add_u64 v[168:169], s[12:13], 0, v[174:175]
	v_mad_i64_i32 v[174:175], s[46:47], s54, v211, v[178:179]
	v_pk_add_f32 v[166:167], v[176:177], v[236:237]
	global_load_dwordx4 v[168:171], v[168:169], off
	global_load_dwordx4 v[174:177], v[174:175], off
	v_mad_i64_i32 v[212:213], s[46:47], s55, v211, v[178:179]
	global_load_dwordx4 v[212:215], v[212:213], off
	v_mad_i64_i32 v[216:217], s[46:47], s53, v211, v[178:179]
	global_load_dwordx4 v[216:219], v[216:217], off
	v_mad_i64_i32 v[220:221], s[46:47], s52, v211, v[178:179]
	global_load_dwordx4 v[220:223], v[220:221], off
	v_mad_i64_i32 v[224:225], s[46:47], s81, v211, v[178:179]
	global_load_dwordx4 v[224:227], v[224:225], off
	v_mad_i64_i32 v[228:229], s[46:47], s80, v211, v[178:179]
	global_load_dwordx4 v[228:231], v[228:229], off
	v_mad_i64_i32 v[232:233], s[46:47], s43, v211, v[178:179]
	global_load_dwordx4 v[232:235], v[232:233], off
	v_mad_i64_i32 v[236:237], s[46:47], s37, v211, v[178:179]
	global_load_dwordx4 v[236:239], v[236:237], off
	v_lshlrev_b64 v[172:173], 2, v[172:173]
	s_waitcnt vmcnt(7)
	v_pk_add_f32 v[174:175], v[168:169], v[174:175]
	v_pk_add_f32 v[176:177], v[170:171], v[176:177]
	s_waitcnt vmcnt(6)
	v_pk_add_f32 v[174:175], v[174:175], v[212:213]
	v_pk_add_f32 v[176:177], v[176:177], v[214:215]
	s_waitcnt vmcnt(5)
	v_pk_add_f32 v[174:175], v[174:175], v[216:217]
	v_pk_add_f32 v[176:177], v[176:177], v[218:219]
	s_waitcnt vmcnt(4)
	v_pk_add_f32 v[174:175], v[174:175], v[220:221]
	v_pk_add_f32 v[176:177], v[176:177], v[222:223]
	s_waitcnt vmcnt(3)
	v_pk_add_f32 v[174:175], v[174:175], v[224:225]
	v_pk_add_f32 v[176:177], v[176:177], v[226:227]
	s_waitcnt vmcnt(2)
	v_pk_add_f32 v[174:175], v[174:175], v[228:229]
	v_pk_add_f32 v[176:177], v[176:177], v[230:231]
	s_waitcnt vmcnt(1)
	v_pk_add_f32 v[204:205], v[174:175], v[232:233]
	v_pk_add_f32 v[170:171], v[176:177], v[234:235]
	v_add_u32_e32 v178, s35, v181
	v_ashrrev_i32_e32 v179, 31, v178
	s_waitcnt vmcnt(0)
	v_pk_add_f32 v[168:169], v[170:171], v[238:239]
	v_pk_add_f32 v[170:171], v[204:205], v[236:237]
	v_lshl_add_u64 v[174:175], s[0:1], 0, v[172:173]
	v_lshlrev_b64 v[176:177], 12, v[178:179]
	v_lshl_add_u64 v[204:205], v[174:175], 0, v[176:177]
	global_load_dwordx4 v[212:215], v[204:205], off
	global_load_dwordx4 v[216:219], v[204:205], off offset:64
	global_load_dwordx4 v[220:223], v[204:205], off offset:512
	global_load_dwordx4 v[224:227], v[204:205], off offset:576
	v_or_b32_e32 v204, 16, v178
	v_ashrrev_i32_e32 v205, 31, v204
	v_lshlrev_b64 v[204:205], 12, v[204:205]
	v_lshl_add_u64 v[206:207], v[174:175], 0, v[204:205]
	global_load_dwordx4 v[228:231], v[206:207], off
	global_load_dwordx4 v[232:235], v[206:207], off offset:64
	global_load_dwordx4 v[236:239], v[206:207], off offset:512
	global_load_dwordx4 v[240:243], v[206:207], off offset:576
	v_lshl_add_u64 v[206:207], s[0:1], 0, v[176:177]
	v_lshl_add_u64 v[206:207], v[206:207], 0, v[172:173]
	s_waitcnt vmcnt(7)
	v_pk_fma_f32 v[126:127], v[126:127], v[156:157], v[214:215]
	v_pk_fma_f32 v[124:125], v[124:125], v[158:159], v[212:213]
	s_waitcnt vmcnt(5)
	v_pk_fma_f32 v[110:111], v[110:111], v[164:165], v[222:223]
	v_pk_fma_f32 v[108:109], v[108:109], v[166:167], v[220:221]
	global_store_dwordx4 v[206:207], v[108:111], off offset:512
	s_waitcnt vmcnt(5)
	v_pk_fma_f32 v[106:107], v[106:107], v[168:169], v[226:227]
	v_pk_fma_f32 v[104:105], v[104:105], v[170:171], v[224:225]
	v_lshl_add_u64 v[108:109], s[0:1], 0, v[204:205]
	v_lshl_add_u64 v[108:109], v[108:109], 0, v[172:173]
	s_waitcnt vmcnt(1)
	v_pk_fma_f32 v[98:99], v[98:99], v[168:169], v[242:243]
	v_pk_fma_f32 v[96:97], v[96:97], v[170:171], v[240:241]
	global_store_dwordx4 v[108:109], v[96:99], off offset:576
	global_store_dwordx4 v[206:207], v[104:107], off offset:576
	v_pk_fma_f32 v[122:123], v[122:123], v[160:161], v[218:219]
	v_or_b32_e32 v96, 32, v178
	v_pk_fma_f32 v[106:107], v[118:119], v[156:157], v[230:231]
	v_pk_fma_f32 v[104:105], v[116:117], v[158:159], v[228:229]
	v_ashrrev_i32_e32 v97, 31, v96
	v_pk_fma_f32 v[120:121], v[120:121], v[162:163], v[216:217]
	global_store_dwordx4 v[108:109], v[104:107], off
	v_pk_fma_f32 v[102:103], v[102:103], v[164:165], v[238:239]
	v_pk_fma_f32 v[100:101], v[100:101], v[166:167], v[236:237]
	v_pk_fma_f32 v[106:107], v[114:115], v[160:161], v[234:235]
	v_pk_fma_f32 v[104:105], v[112:113], v[162:163], v[232:233]
	v_lshlrev_b64 v[204:205], 12, v[96:97]
	v_or_b32_e32 v112, 48, v178
	global_store_dwordx4 v[206:207], v[124:127], off
	global_store_dwordx4 v[206:207], v[120:123], off offset:64
	global_store_dwordx4 v[108:109], v[104:107], off offset:64
	global_store_dwordx4 v[108:109], v[100:103], off offset:512
	v_lshl_add_u64 v[108:109], v[174:175], 0, v[204:205]
	v_ashrrev_i32_e32 v113, 31, v112
	global_load_dwordx4 v[96:99], v[108:109], off
	global_load_dwordx4 v[100:103], v[108:109], off offset:64
	global_load_dwordx4 v[104:107], v[108:109], off offset:512
	s_nop 0
	global_load_dwordx4 v[108:111], v[108:109], off offset:576
	v_lshlrev_b64 v[178:179], 12, v[112:113]
	v_lshl_add_u64 v[124:125], v[174:175], 0, v[178:179]
	global_load_dwordx4 v[112:115], v[124:125], off
	global_load_dwordx4 v[116:119], v[124:125], off offset:64
	global_load_dwordx4 v[120:123], v[124:125], off offset:512
	s_nop 0
	global_load_dwordx4 v[124:127], v[124:125], off offset:576
	s_waitcnt vmcnt(7)
	v_pk_fma_f32 v[92:93], v[92:93], v[158:159], v[96:97]
	v_lshl_add_u64 v[96:97], s[0:1], 0, v[204:205]
	v_lshl_add_u64 v[96:97], v[96:97], 0, v[172:173]
	s_waitcnt vmcnt(5)
	v_pk_fma_f32 v[78:79], v[78:79], v[164:165], v[106:107]
	v_pk_fma_f32 v[76:77], v[76:77], v[166:167], v[104:105]
	global_store_dwordx4 v[96:97], v[76:79], off offset:512
	s_waitcnt vmcnt(5)
	v_pk_fma_f32 v[74:75], v[74:75], v[168:169], v[110:111]
	v_pk_fma_f32 v[72:73], v[72:73], v[170:171], v[108:109]
	v_lshl_add_u64 v[76:77], s[0:1], 0, v[178:179]
	v_pk_fma_f32 v[94:95], v[94:95], v[156:157], v[98:99]
	v_pk_fma_f32 v[90:91], v[90:91], v[160:161], v[102:103]
	v_pk_fma_f32 v[88:89], v[88:89], v[162:163], v[100:101]
	global_store_dwordx4 v[96:97], v[72:75], off offset:576
	v_lshl_add_u64 v[76:77], v[76:77], 0, v[172:173]
	global_store_dwordx4 v[96:97], v[92:95], off
	s_waitcnt vmcnt(6)
	v_pk_fma_f32 v[74:75], v[86:87], v[156:157], v[114:115]
	v_pk_fma_f32 v[72:73], v[84:85], v[158:159], v[112:113]
	global_store_dwordx4 v[96:97], v[88:91], off offset:64
	global_store_dwordx4 v[76:77], v[72:75], off
	s_waitcnt vmcnt(6)
	v_pk_fma_f32 v[70:71], v[70:71], v[164:165], v[122:123]
	v_pk_fma_f32 v[68:69], v[68:69], v[166:167], v[120:121]
	v_pk_fma_f32 v[74:75], v[82:83], v[160:161], v[118:119]
	v_pk_fma_f32 v[72:73], v[80:81], v[162:163], v[116:117]
	s_waitcnt vmcnt(5)
	v_pk_fma_f32 v[66:67], v[66:67], v[168:169], v[126:127]
	v_pk_fma_f32 v[64:65], v[64:65], v[170:171], v[124:125]
	v_lshl_add_u64 v[96:97], v[176:177], 0, s[20:21]
	global_store_dwordx4 v[76:77], v[72:75], off offset:64
	global_store_dwordx4 v[76:77], v[68:71], off offset:512
	global_store_dwordx4 v[76:77], v[64:67], off offset:576
	v_lshl_add_u64 v[76:77], v[174:175], 0, v[96:97]
	global_load_dwordx4 v[64:67], v[76:77], off
	global_load_dwordx4 v[68:71], v[76:77], off offset:64
	global_load_dwordx4 v[72:75], v[76:77], off offset:512
	s_nop 0
	global_load_dwordx4 v[76:79], v[76:77], off offset:576
	v_lshl_add_u64 v[98:99], v[176:177], 0, s[22:23]
	v_lshl_add_u64 v[92:93], v[174:175], 0, v[98:99]
	global_load_dwordx4 v[80:83], v[92:93], off
	global_load_dwordx4 v[84:87], v[92:93], off offset:64
	global_load_dwordx4 v[88:91], v[92:93], off offset:512
	s_nop 0
	global_load_dwordx4 v[92:95], v[92:93], off offset:576
	s_waitcnt vmcnt(7)
	v_pk_fma_f32 v[60:61], v[60:61], v[158:159], v[64:65]
	v_lshl_add_u64 v[64:65], s[0:1], 0, v[96:97]
	v_lshl_add_u64 v[64:65], v[64:65], 0, v[172:173]
	s_waitcnt vmcnt(5)
	v_pk_fma_f32 v[46:47], v[46:47], v[164:165], v[74:75]
	v_pk_fma_f32 v[44:45], v[44:45], v[166:167], v[72:73]
	global_store_dwordx4 v[64:65], v[44:47], off offset:512
	s_waitcnt vmcnt(5)
	v_pk_fma_f32 v[42:43], v[42:43], v[168:169], v[78:79]
	v_pk_fma_f32 v[40:41], v[40:41], v[170:171], v[76:77]
	v_lshl_add_u64 v[44:45], s[0:1], 0, v[98:99]
	global_store_dwordx4 v[64:65], v[40:43], off offset:576
	v_lshl_add_u64 v[44:45], v[44:45], 0, v[172:173]
	v_pk_fma_f32 v[62:63], v[62:63], v[156:157], v[66:67]
	s_waitcnt vmcnt(5)
	v_pk_fma_f32 v[42:43], v[54:55], v[156:157], v[82:83]
	v_pk_fma_f32 v[40:41], v[52:53], v[158:159], v[80:81]
	v_pk_fma_f32 v[58:59], v[58:59], v[160:161], v[70:71]
	v_pk_fma_f32 v[56:57], v[56:57], v[162:163], v[68:69]
	global_store_dwordx4 v[44:45], v[40:43], off
	s_waitcnt vmcnt(4)
	v_pk_fma_f32 v[38:39], v[38:39], v[164:165], v[90:91]
	v_pk_fma_f32 v[36:37], v[36:37], v[166:167], v[88:89]
	v_pk_fma_f32 v[42:43], v[50:51], v[160:161], v[86:87]
	v_pk_fma_f32 v[40:41], v[48:49], v[162:163], v[84:85]
	s_waitcnt vmcnt(3)
	v_pk_fma_f32 v[34:35], v[34:35], v[168:169], v[94:95]
	v_pk_fma_f32 v[32:33], v[32:33], v[170:171], v[92:93]
	v_lshl_add_u64 v[66:67], v[176:177], 0, s[24:25]
	global_store_dwordx4 v[64:65], v[60:63], off
	global_store_dwordx4 v[64:65], v[56:59], off offset:64
	global_store_dwordx4 v[44:45], v[40:43], off offset:64
	global_store_dwordx4 v[44:45], v[36:39], off offset:512
	global_store_dwordx4 v[44:45], v[32:35], off offset:576
	v_lshl_add_u64 v[64:65], v[176:177], 0, s[26:27]
	v_lshl_add_u64 v[36:37], v[174:175], 0, v[64:65]
	v_lshl_add_u64 v[32:33], v[174:175], 0, v[66:67]
	global_load_dwordx4 v[48:51], v[32:33], off
	global_load_dwordx4 v[60:63], v[32:33], off offset:64
	global_load_dwordx4 v[56:59], v[32:33], off offset:512
	global_load_dwordx4 v[52:55], v[32:33], off offset:576
	s_nop 0
	global_load_dwordx4 v[32:35], v[36:37], off
	global_load_dwordx4 v[44:47], v[36:37], off offset:64
	global_load_dwordx4 v[40:43], v[36:37], off offset:512
	s_nop 0
	global_load_dwordx4 v[36:39], v[36:37], off offset:576
	s_waitcnt vmcnt(7)
	v_pk_fma_f32 v[28:29], v[28:29], v[158:159], v[48:49]
	v_lshl_add_u64 v[48:49], s[0:1], 0, v[66:67]
	v_lshl_add_u64 v[48:49], v[48:49], 0, v[172:173]
	s_waitcnt vmcnt(5)
	v_pk_fma_f32 v[18:19], v[18:19], v[164:165], v[58:59]
	v_pk_fma_f32 v[16:17], v[16:17], v[166:167], v[56:57]
	global_store_dwordx4 v[48:49], v[16:19], off offset:512
	s_waitcnt vmcnt(5)
	v_pk_fma_f32 v[10:11], v[10:11], v[168:169], v[54:55]
	v_pk_fma_f32 v[8:9], v[8:9], v[170:171], v[52:53]
	v_lshl_add_u64 v[16:17], s[0:1], 0, v[64:65]
	global_store_dwordx4 v[48:49], v[8:11], off offset:576
	v_lshl_add_u64 v[16:17], v[16:17], 0, v[172:173]
	v_pk_fma_f32 v[30:31], v[30:31], v[156:157], v[50:51]
	s_waitcnt vmcnt(5)
	v_pk_fma_f32 v[10:11], v[22:23], v[156:157], v[34:35]
	v_pk_fma_f32 v[8:9], v[20:21], v[158:159], v[32:33]
	v_pk_fma_f32 v[26:27], v[26:27], v[160:161], v[62:63]
	v_pk_fma_f32 v[24:25], v[24:25], v[162:163], v[60:61]
	global_store_dwordx4 v[16:17], v[8:11], off
	s_waitcnt vmcnt(4)
	v_pk_fma_f32 v[6:7], v[6:7], v[164:165], v[42:43]
	v_pk_fma_f32 v[4:5], v[4:5], v[166:167], v[40:41]
	v_pk_fma_f32 v[10:11], v[14:15], v[160:161], v[46:47]
	v_pk_fma_f32 v[8:9], v[12:13], v[162:163], v[44:45]
	s_waitcnt vmcnt(3)
	v_pk_fma_f32 v[2:3], v[2:3], v[168:169], v[38:39]
	v_pk_fma_f32 v[0:1], v[0:1], v[170:171], v[36:37]
	global_store_dwordx4 v[48:49], v[28:31], off
	global_store_dwordx4 v[48:49], v[24:27], off offset:64
	global_store_dwordx4 v[16:17], v[8:11], off offset:64
	global_store_dwordx4 v[16:17], v[4:7], off offset:512
	global_store_dwordx4 v[16:17], v[0:3], off offset:576
	s_waitcnt vmcnt(0)
	s_barrier
	s_and_saveexec_b64 s[46:47], s[4:5]
	s_cbranch_execz .LBB0_1188
	s_lshl_b32 s48, s44, 2
	s_ashr_i32 s49, s48, 31
	s_lshl_b64 s[48:49], s[48:49], 2
	s_add_u32 s48, s72, s48
	s_addc_u32 s49, s73, s49
	s_getreg_b32 s45, hwreg(HW_REG_XCC_ID, 0, 4)
	global_load_dwordx4 v[0:3], v131, s[48:49]
	s_and_b32 s45, s45, 15
	s_add_i32 s45, s45, 1
	s_waitcnt vmcnt(0)
	v_cmp_ne_u32_e32 vcc, s45, v2
	s_nop 1
	v_cndmask_b32_e64 v2, 0, 1, vcc
	v_cmp_ne_u32_e32 vcc, s45, v3
	v_lshlrev_b32_e32 v2, 2, v2
	s_nop 0
	v_cndmask_b32_e64 v3, 0, 1, vcc
	v_cmp_ne_u32_e32 vcc, s45, v1
	v_lshlrev_b32_e32 v3, 3, v3
	v_or_b32_e32 v2, v3, v2
	v_cndmask_b32_e64 v1, 0, 1, vcc
	v_cmp_ne_u32_e32 vcc, s45, v0
	v_lshlrev_b32_e32 v1, 1, v1
	s_nop 0
	v_cndmask_b32_e64 v0, 0, 1, vcc
	v_or_b32_e32 v0, v0, v1
	v_and_b32_e32 v0, 3, v0
	v_or_b32_e32 v0, v0, v2
	v_and_b32_e32 v0, 15, v0
	v_cmp_eq_u32_e32 vcc, 0, v0
	s_cbranch_vccnz .LBB0_1177
	buffer_wbl2 sc1
	s_waitcnt vmcnt(0)

.LBB0_1484:
	v_lshl_or_b32 v172, s66, 8, v198
	v_add_u32_e32 v156, 0x2000, v172
	v_ashrrev_i32_e32 v157, 31, v156
	v_lshlrev_b64 v[160:161], 2, v[156:157]
	s_ashr_i32 s69, s67, 3
	v_lshl_add_u64 v[164:165], s[14:15], 0, v[160:161]
	v_lshl_add_u64 v[156:157], s[16:17], 0, v[160:161]
	v_mad_i64_i32 v[160:161], s[70:71], s69, v211, v[164:165]
	global_load_dwordx4 v[156:159], v[156:157], off
	s_add_i32 s42, s69, 8
	s_add_i32 s41, s69, 16
	s_add_i32 s40, s69, 24
	s_add_i32 s39, s69, 32
	s_add_i32 s38, s69, 40
	s_add_i32 s37, s69, 48
	s_add_i32 s36, s69, 56
	s_lshl_b32 s68, s67, 8
	global_load_dwordx4 v[160:163], v[160:161], off
	v_mad_i64_i32 v[212:213], s[70:71], s42, v211, v[164:165]
	global_load_dwordx4 v[212:215], v[212:213], off
	v_mad_i64_i32 v[216:217], s[70:71], s41, v211, v[164:165]
	global_load_dwordx4 v[216:219], v[216:217], off
	v_mad_i64_i32 v[220:221], s[70:71], s40, v211, v[164:165]
	global_load_dwordx4 v[220:223], v[220:221], off
	v_mad_i64_i32 v[224:225], s[70:71], s39, v211, v[164:165]
	global_load_dwordx4 v[224:227], v[224:225], off
	v_mad_i64_i32 v[228:229], s[70:71], s38, v211, v[164:165]
	global_load_dwordx4 v[228:231], v[228:229], off
	v_mad_i64_i32 v[232:233], s[70:71], s37, v211, v[164:165]
	global_load_dwordx4 v[232:235], v[232:233], off
	v_mad_i64_i32 v[236:237], s[70:71], s36, v211, v[164:165]
	global_load_dwordx4 v[236:239], v[236:237], off
	v_ashrrev_i32_e32 v173, 31, v172
	s_waitcnt vmcnt(7)
	v_pk_add_f32 v[160:161], v[156:157], v[160:161]
	v_pk_add_f32 v[162:163], v[158:159], v[162:163]
	s_waitcnt vmcnt(6)
	v_pk_add_f32 v[160:161], v[160:161], v[212:213]
	v_pk_add_f32 v[162:163], v[162:163], v[214:215]
	s_waitcnt vmcnt(5)
	v_pk_add_f32 v[160:161], v[160:161], v[216:217]
	v_pk_add_f32 v[162:163], v[162:163], v[218:219]
	s_waitcnt vmcnt(4)
	v_pk_add_f32 v[160:161], v[160:161], v[220:221]
	v_pk_add_f32 v[162:163], v[162:163], v[222:223]
	s_waitcnt vmcnt(3)
	v_pk_add_f32 v[160:161], v[160:161], v[224:225]
	v_pk_add_f32 v[162:163], v[162:163], v[226:227]
	s_waitcnt vmcnt(2)
	v_pk_add_f32 v[160:161], v[160:161], v[228:229]
	v_pk_add_f32 v[162:163], v[162:163], v[230:231]
	s_waitcnt vmcnt(1)
	v_pk_add_f32 v[160:161], v[160:161], v[232:233]
	v_pk_add_f32 v[162:163], v[162:163], v[234:235]
	s_waitcnt vmcnt(0)
	v_pk_add_f32 v[158:159], v[162:163], v[238:239]
	v_pk_add_f32 v[160:161], v[160:161], v[236:237]
	v_pk_mul_f32 v[156:157], v[158:159], 0.5 op_sel_hi:[1, 0]
	v_pk_mul_f32 v[158:159], v[160:161], 0.5 op_sel_hi:[1, 0]
	v_add_u32_e32 v160, 0x2010, v172
	v_ashrrev_i32_e32 v161, 31, v160
	v_lshlrev_b64 v[164:165], 2, v[160:161]
	v_lshl_add_u64 v[168:169], s[14:15], 0, v[164:165]
	v_lshl_add_u64 v[160:161], s[16:17], 0, v[164:165]
	v_mad_i64_i32 v[164:165], s[70:71], s69, v211, v[168:169]
	global_load_dwordx4 v[160:163], v[160:161], off
	global_load_dwordx4 v[164:167], v[164:165], off
	v_mad_i64_i32 v[212:213], s[70:71], s42, v211, v[168:169]
	global_load_dwordx4 v[212:215], v[212:213], off
	v_mad_i64_i32 v[216:217], s[70:71], s41, v211, v[168:169]
	global_load_dwordx4 v[216:219], v[216:217], off
	v_mad_i64_i32 v[220:221], s[70:71], s40, v211, v[168:169]
	global_load_dwordx4 v[220:223], v[220:221], off
	v_mad_i64_i32 v[224:225], s[70:71], s39, v211, v[168:169]
	global_load_dwordx4 v[224:227], v[224:225], off
	v_mad_i64_i32 v[228:229], s[70:71], s38, v211, v[168:169]
	global_load_dwordx4 v[228:231], v[228:229], off
	v_mad_i64_i32 v[232:233], s[70:71], s37, v211, v[168:169]
	global_load_dwordx4 v[232:235], v[232:233], off
	v_mad_i64_i32 v[236:237], s[70:71], s36, v211, v[168:169]
	global_load_dwordx4 v[236:239], v[236:237], off
	s_waitcnt vmcnt(7)
	v_pk_add_f32 v[164:165], v[160:161], v[164:165]
	v_pk_add_f32 v[166:167], v[162:163], v[166:167]
	s_waitcnt vmcnt(6)
	v_pk_add_f32 v[164:165], v[164:165], v[212:213]
	v_pk_add_f32 v[166:167], v[166:167], v[214:215]
	s_waitcnt vmcnt(5)
	v_pk_add_f32 v[164:165], v[164:165], v[216:217]
	v_pk_add_f32 v[166:167], v[166:167], v[218:219]
	s_waitcnt vmcnt(4)
	v_pk_add_f32 v[164:165], v[164:165], v[220:221]
	v_pk_add_f32 v[166:167], v[166:167], v[222:223]
	s_waitcnt vmcnt(3)
	v_pk_add_f32 v[164:165], v[164:165], v[224:225]
	v_pk_add_f32 v[166:167], v[166:167], v[226:227]
	s_waitcnt vmcnt(2)
	v_pk_add_f32 v[164:165], v[164:165], v[228:229]
	v_pk_add_f32 v[166:167], v[166:167], v[230:231]
	s_waitcnt vmcnt(1)
	v_pk_add_f32 v[164:165], v[164:165], v[232:233]
	v_pk_add_f32 v[166:167], v[166:167], v[234:235]
	s_waitcnt vmcnt(0)
	v_pk_add_f32 v[162:163], v[166:167], v[238:239]
	v_pk_add_f32 v[164:165], v[164:165], v[236:237]
	v_pk_mul_f32 v[160:161], v[162:163], 0.5 op_sel_hi:[1, 0]
	v_pk_mul_f32 v[162:163], v[164:165], 0.5 op_sel_hi:[1, 0]
	v_add_u32_e32 v164, 0x2080, v172
	v_ashrrev_i32_e32 v165, 31, v164
	v_lshlrev_b64 v[168:169], 2, v[164:165]
	v_lshl_add_u64 v[174:175], s[14:15], 0, v[168:169]
	v_lshl_add_u64 v[164:165], s[16:17], 0, v[168:169]
	v_mad_i64_i32 v[168:169], s[70:71], s69, v211, v[174:175]
	global_load_dwordx4 v[164:167], v[164:165], off
	global_load_dwordx4 v[168:171], v[168:169], off
	v_mad_i64_i32 v[212:213], s[70:71], s42, v211, v[174:175]
	global_load_dwordx4 v[212:215], v[212:213], off
	v_mad_i64_i32 v[216:217], s[70:71], s41, v211, v[174:175]
	global_load_dwordx4 v[216:219], v[216:217], off
	v_mad_i64_i32 v[220:221], s[70:71], s40, v211, v[174:175]
	global_load_dwordx4 v[220:223], v[220:221], off
	v_mad_i64_i32 v[224:225], s[70:71], s39, v211, v[174:175]
	global_load_dwordx4 v[224:227], v[224:225], off
	v_mad_i64_i32 v[228:229], s[70:71], s38, v211, v[174:175]
	global_load_dwordx4 v[228:231], v[228:229], off
	v_mad_i64_i32 v[232:233], s[70:71], s37, v211, v[174:175]
	global_load_dwordx4 v[232:235], v[232:233], off
	v_mad_i64_i32 v[236:237], s[70:71], s36, v211, v[174:175]
	global_load_dwordx4 v[236:239], v[236:237], off
	s_waitcnt vmcnt(7)
	v_pk_add_f32 v[168:169], v[164:165], v[168:169]
	v_pk_add_f32 v[170:171], v[166:167], v[170:171]
	s_waitcnt vmcnt(6)
	v_pk_add_f32 v[168:169], v[168:169], v[212:213]
	v_pk_add_f32 v[170:171], v[170:171], v[214:215]
	s_waitcnt vmcnt(5)
	v_pk_add_f32 v[168:169], v[168:169], v[216:217]
	v_pk_add_f32 v[170:171], v[170:171], v[218:219]
	s_waitcnt vmcnt(4)
	v_pk_add_f32 v[168:169], v[168:169], v[220:221]
	v_pk_add_f32 v[170:171], v[170:171], v[222:223]
	s_waitcnt vmcnt(3)
	v_pk_add_f32 v[168:169], v[168:169], v[224:225]
	v_pk_add_f32 v[170:171], v[170:171], v[226:227]
	s_waitcnt vmcnt(2)
	v_pk_add_f32 v[168:169], v[168:169], v[228:229]
	v_pk_add_f32 v[170:171], v[170:171], v[230:231]
	s_waitcnt vmcnt(1)
	v_pk_add_f32 v[168:169], v[168:169], v[232:233]
	v_pk_add_f32 v[170:171], v[170:171], v[234:235]
	s_waitcnt vmcnt(0)
	v_pk_add_f32 v[166:167], v[170:171], v[238:239]
	v_pk_add_f32 v[168:169], v[168:169], v[236:237]
	v_pk_mul_f32 v[164:165], v[166:167], 0.5 op_sel_hi:[1, 0]
	v_pk_mul_f32 v[166:167], v[168:169], 0.5 op_sel_hi:[1, 0]
	v_add_u32_e32 v168, 0x2090, v172
	v_ashrrev_i32_e32 v169, 31, v168
	v_lshlrev_b64 v[174:175], 2, v[168:169]
	v_lshl_add_u64 v[178:179], s[14:15], 0, v[174:175]
	v_lshl_add_u64 v[168:169], s[16:17], 0, v[174:175]
	v_mad_i64_i32 v[174:175], s[70:71], s69, v211, v[178:179]
	global_load_dwordx4 v[168:171], v[168:169], off
	global_load_dwordx4 v[174:177], v[174:175], off
	v_mad_i64_i32 v[212:213], s[42:43], s42, v211, v[178:179]
	global_load_dwordx4 v[212:215], v[212:213], off
	v_mad_i64_i32 v[216:217], s[42:43], s41, v211, v[178:179]
	global_load_dwordx4 v[216:219], v[216:217], off
	v_mad_i64_i32 v[220:221], s[40:41], s40, v211, v[178:179]
	global_load_dwordx4 v[220:223], v[220:221], off
	v_mad_i64_i32 v[224:225], s[40:41], s39, v211, v[178:179]
	global_load_dwordx4 v[224:227], v[224:225], off
	v_mad_i64_i32 v[228:229], s[38:39], s38, v211, v[178:179]
	global_load_dwordx4 v[228:231], v[228:229], off
	v_mad_i64_i32 v[232:233], s[38:39], s37, v211, v[178:179]
	global_load_dwordx4 v[232:235], v[232:233], off
	v_mad_i64_i32 v[236:237], s[36:37], s36, v211, v[178:179]
	global_load_dwordx4 v[236:239], v[236:237], off
	v_lshlrev_b64 v[172:173], 2, v[172:173]
	v_readfirstlane_b32 s70, v180
	s_waitcnt vmcnt(7)
	v_pk_add_f32 v[174:175], v[168:169], v[174:175]
	v_pk_add_f32 v[176:177], v[170:171], v[176:177]
	s_waitcnt vmcnt(6)
	v_pk_add_f32 v[174:175], v[174:175], v[212:213]
	v_pk_add_f32 v[176:177], v[176:177], v[214:215]
	s_waitcnt vmcnt(5)
	v_pk_add_f32 v[174:175], v[174:175], v[216:217]
	v_pk_add_f32 v[176:177], v[176:177], v[218:219]
	s_waitcnt vmcnt(4)
	v_pk_add_f32 v[174:175], v[174:175], v[220:221]
	v_pk_add_f32 v[176:177], v[176:177], v[222:223]
	s_waitcnt vmcnt(3)
	v_pk_add_f32 v[174:175], v[174:175], v[224:225]
	v_pk_add_f32 v[176:177], v[176:177], v[226:227]
	s_waitcnt vmcnt(2)
	v_pk_add_f32 v[174:175], v[174:175], v[228:229]
	v_pk_add_f32 v[176:177], v[176:177], v[230:231]
	s_waitcnt vmcnt(1)
	v_pk_add_f32 v[174:175], v[174:175], v[232:233]
	v_pk_add_f32 v[176:177], v[176:177], v[234:235]
	v_add_u32_e32 v178, s68, v181
	v_ashrrev_i32_e32 v179, 31, v178
	s_waitcnt vmcnt(0)
	v_pk_add_f32 v[170:171], v[176:177], v[238:239]
	v_pk_add_f32 v[174:175], v[174:175], v[236:237]
	v_pk_mul_f32 v[168:169], v[170:171], 0.5 op_sel_hi:[1, 0]
	v_pk_mul_f32 v[170:171], v[174:175], 0.5 op_sel_hi:[1, 0]
	v_lshl_add_u64 v[174:175], s[12:13], 0, v[172:173]
	v_lshlrev_b64 v[176:177], 12, v[178:179]
	v_lshl_add_u64 v[204:205], v[174:175], 0, v[176:177]
	global_load_dwordx4 v[212:215], v[204:205], off
	global_load_dwordx4 v[216:219], v[204:205], off offset:64
	global_load_dwordx4 v[220:223], v[204:205], off offset:512
	global_load_dwordx4 v[224:227], v[204:205], off offset:576
	v_or_b32_e32 v204, 16, v178
	v_ashrrev_i32_e32 v205, 31, v204
	v_lshlrev_b64 v[204:205], 12, v[204:205]
	v_lshl_add_u64 v[206:207], v[174:175], 0, v[204:205]
	global_load_dwordx4 v[228:231], v[206:207], off
	global_load_dwordx4 v[232:235], v[206:207], off offset:64
	global_load_dwordx4 v[236:239], v[206:207], off offset:512
	global_load_dwordx4 v[240:243], v[206:207], off offset:576
	v_lshl_add_u64 v[206:207], s[12:13], 0, v[176:177]
	v_lshl_add_u64 v[206:207], v[206:207], 0, v[172:173]
	s_waitcnt vmcnt(7)
	v_pk_fma_f32 v[126:127], v[126:127], v[156:157], v[214:215]
	v_pk_fma_f32 v[124:125], v[124:125], v[158:159], v[212:213]
	s_waitcnt vmcnt(5)
	v_pk_fma_f32 v[110:111], v[110:111], v[164:165], v[222:223]
	v_pk_fma_f32 v[108:109], v[108:109], v[166:167], v[220:221]
	global_store_dwordx4 v[206:207], v[108:111], off offset:512
	s_waitcnt vmcnt(5)
	v_pk_fma_f32 v[106:107], v[106:107], v[168:169], v[226:227]
	v_pk_fma_f32 v[104:105], v[104:105], v[170:171], v[224:225]
	v_lshl_add_u64 v[108:109], s[12:13], 0, v[204:205]
	v_lshl_add_u64 v[108:109], v[108:109], 0, v[172:173]
	s_waitcnt vmcnt(1)
	v_pk_fma_f32 v[98:99], v[98:99], v[168:169], v[242:243]
	v_pk_fma_f32 v[96:97], v[96:97], v[170:171], v[240:241]
	global_store_dwordx4 v[108:109], v[96:99], off offset:576
	global_store_dwordx4 v[206:207], v[104:107], off offset:576
	v_pk_fma_f32 v[122:123], v[122:123], v[160:161], v[218:219]
	v_or_b32_e32 v96, 32, v178
	v_pk_fma_f32 v[106:107], v[118:119], v[156:157], v[230:231]
	v_pk_fma_f32 v[104:105], v[116:117], v[158:159], v[228:229]
	v_ashrrev_i32_e32 v97, 31, v96
	v_pk_fma_f32 v[120:121], v[120:121], v[162:163], v[216:217]
	global_store_dwordx4 v[108:109], v[104:107], off
	v_pk_fma_f32 v[102:103], v[102:103], v[164:165], v[238:239]
	v_pk_fma_f32 v[100:101], v[100:101], v[166:167], v[236:237]
	v_pk_fma_f32 v[106:107], v[114:115], v[160:161], v[234:235]
	v_pk_fma_f32 v[104:105], v[112:113], v[162:163], v[232:233]
	v_lshlrev_b64 v[204:205], 12, v[96:97]
	v_or_b32_e32 v112, 48, v178
	global_store_dwordx4 v[206:207], v[124:127], off
	global_store_dwordx4 v[206:207], v[120:123], off offset:64
	global_store_dwordx4 v[108:109], v[104:107], off offset:64
	global_store_dwordx4 v[108:109], v[100:103], off offset:512
	v_lshl_add_u64 v[108:109], v[174:175], 0, v[204:205]
	v_ashrrev_i32_e32 v113, 31, v112
	global_load_dwordx4 v[96:99], v[108:109], off
	global_load_dwordx4 v[100:103], v[108:109], off offset:64
	global_load_dwordx4 v[104:107], v[108:109], off offset:512
	s_nop 0
	global_load_dwordx4 v[108:111], v[108:109], off offset:576
	v_lshlrev_b64 v[178:179], 12, v[112:113]
	v_lshl_add_u64 v[124:125], v[174:175], 0, v[178:179]
	global_load_dwordx4 v[112:115], v[124:125], off
	global_load_dwordx4 v[116:119], v[124:125], off offset:64
	global_load_dwordx4 v[120:123], v[124:125], off offset:512
	s_nop 0
	global_load_dwordx4 v[124:127], v[124:125], off offset:576
	s_waitcnt vmcnt(7)
	v_pk_fma_f32 v[92:93], v[92:93], v[158:159], v[96:97]
	v_lshl_add_u64 v[96:97], s[12:13], 0, v[204:205]
	v_lshl_add_u64 v[96:97], v[96:97], 0, v[172:173]
	s_waitcnt vmcnt(5)
	v_pk_fma_f32 v[78:79], v[78:79], v[164:165], v[106:107]
	v_pk_fma_f32 v[76:77], v[76:77], v[166:167], v[104:105]
	global_store_dwordx4 v[96:97], v[76:79], off offset:512
	s_waitcnt vmcnt(5)
	v_pk_fma_f32 v[74:75], v[74:75], v[168:169], v[110:111]
	v_pk_fma_f32 v[72:73], v[72:73], v[170:171], v[108:109]
	v_lshl_add_u64 v[76:77], s[12:13], 0, v[178:179]
	v_pk_fma_f32 v[94:95], v[94:95], v[156:157], v[98:99]
	v_pk_fma_f32 v[90:91], v[90:91], v[160:161], v[102:103]
	v_pk_fma_f32 v[88:89], v[88:89], v[162:163], v[100:101]
	global_store_dwordx4 v[96:97], v[72:75], off offset:576
	v_lshl_add_u64 v[76:77], v[76:77], 0, v[172:173]
	global_store_dwordx4 v[96:97], v[92:95], off
	s_waitcnt vmcnt(6)
	v_pk_fma_f32 v[74:75], v[86:87], v[156:157], v[114:115]
	v_pk_fma_f32 v[72:73], v[84:85], v[158:159], v[112:113]
	global_store_dwordx4 v[96:97], v[88:91], off offset:64
	global_store_dwordx4 v[76:77], v[72:75], off
	s_waitcnt vmcnt(6)
	v_pk_fma_f32 v[70:71], v[70:71], v[164:165], v[122:123]
	v_pk_fma_f32 v[68:69], v[68:69], v[166:167], v[120:121]
	v_pk_fma_f32 v[74:75], v[82:83], v[160:161], v[118:119]
	v_pk_fma_f32 v[72:73], v[80:81], v[162:163], v[116:117]
	s_waitcnt vmcnt(5)
	v_pk_fma_f32 v[66:67], v[66:67], v[168:169], v[126:127]
	v_pk_fma_f32 v[64:65], v[64:65], v[170:171], v[124:125]
	v_lshl_add_u64 v[96:97], v[176:177], 0, s[20:21]
	global_store_dwordx4 v[76:77], v[72:75], off offset:64
	global_store_dwordx4 v[76:77], v[68:71], off offset:512
	global_store_dwordx4 v[76:77], v[64:67], off offset:576
	v_lshl_add_u64 v[76:77], v[174:175], 0, v[96:97]
	global_load_dwordx4 v[64:67], v[76:77], off
	global_load_dwordx4 v[68:71], v[76:77], off offset:64
	global_load_dwordx4 v[72:75], v[76:77], off offset:512
	s_nop 0
	global_load_dwordx4 v[76:79], v[76:77], off offset:576
	v_lshl_add_u64 v[98:99], v[176:177], 0, s[22:23]
	v_lshl_add_u64 v[92:93], v[174:175], 0, v[98:99]
	global_load_dwordx4 v[80:83], v[92:93], off
	global_load_dwordx4 v[84:87], v[92:93], off offset:64
	global_load_dwordx4 v[88:91], v[92:93], off offset:512
	s_nop 0
	global_load_dwordx4 v[92:95], v[92:93], off offset:576
	s_waitcnt vmcnt(7)
	v_pk_fma_f32 v[60:61], v[60:61], v[158:159], v[64:65]
	v_lshl_add_u64 v[64:65], s[12:13], 0, v[96:97]
	v_lshl_add_u64 v[64:65], v[64:65], 0, v[172:173]
	s_waitcnt vmcnt(5)
	v_pk_fma_f32 v[46:47], v[46:47], v[164:165], v[74:75]
	v_pk_fma_f32 v[44:45], v[44:45], v[166:167], v[72:73]
	global_store_dwordx4 v[64:65], v[44:47], off offset:512
	s_waitcnt vmcnt(5)
	v_pk_fma_f32 v[42:43], v[42:43], v[168:169], v[78:79]
	v_pk_fma_f32 v[40:41], v[40:41], v[170:171], v[76:77]
	v_lshl_add_u64 v[44:45], s[12:13], 0, v[98:99]
	v_pk_fma_f32 v[62:63], v[62:63], v[156:157], v[66:67]
	v_pk_fma_f32 v[58:59], v[58:59], v[160:161], v[70:71]
	v_pk_fma_f32 v[56:57], v[56:57], v[162:163], v[68:69]
	global_store_dwordx4 v[64:65], v[40:43], off offset:576
	v_lshl_add_u64 v[44:45], v[44:45], 0, v[172:173]
	global_store_dwordx4 v[64:65], v[60:63], off
	s_waitcnt vmcnt(6)
	v_pk_fma_f32 v[42:43], v[54:55], v[156:157], v[82:83]
	v_pk_fma_f32 v[40:41], v[52:53], v[158:159], v[80:81]
	global_store_dwordx4 v[64:65], v[56:59], off offset:64
	global_store_dwordx4 v[44:45], v[40:43], off
	s_waitcnt vmcnt(6)
	v_pk_fma_f32 v[38:39], v[38:39], v[164:165], v[90:91]
	v_pk_fma_f32 v[36:37], v[36:37], v[166:167], v[88:89]
	v_pk_fma_f32 v[42:43], v[50:51], v[160:161], v[86:87]
	v_pk_fma_f32 v[40:41], v[48:49], v[162:163], v[84:85]
	s_waitcnt vmcnt(5)
	v_pk_fma_f32 v[34:35], v[34:35], v[168:169], v[94:95]
	v_pk_fma_f32 v[32:33], v[32:33], v[170:171], v[92:93]
	v_lshl_add_u64 v[64:65], v[176:177], 0, s[24:25]
	global_store_dwordx4 v[44:45], v[40:43], off offset:64
	global_store_dwordx4 v[44:45], v[36:39], off offset:512
	global_store_dwordx4 v[44:45], v[32:35], off offset:576
	v_lshl_add_u64 v[44:45], v[174:175], 0, v[64:65]
	global_load_dwordx4 v[32:35], v[44:45], off
	global_load_dwordx4 v[36:39], v[44:45], off offset:64
	global_load_dwordx4 v[40:43], v[44:45], off offset:512
	s_nop 0
	global_load_dwordx4 v[44:47], v[44:45], off offset:576
	v_lshl_add_u64 v[66:67], v[176:177], 0, s[26:27]
	v_lshl_add_u64 v[60:61], v[174:175], 0, v[66:67]
	global_load_dwordx4 v[48:51], v[60:61], off
	global_load_dwordx4 v[52:55], v[60:61], off offset:64
	global_load_dwordx4 v[56:59], v[60:61], off offset:512
	s_nop 0
	global_load_dwordx4 v[60:63], v[60:61], off offset:576
	s_waitcnt vmcnt(7)
	v_pk_fma_f32 v[28:29], v[28:29], v[158:159], v[32:33]
	v_lshl_add_u64 v[32:33], s[12:13], 0, v[64:65]
	v_lshl_add_u64 v[32:33], v[32:33], 0, v[172:173]
	s_waitcnt vmcnt(5)
	v_pk_fma_f32 v[18:19], v[18:19], v[164:165], v[42:43]
	v_pk_fma_f32 v[16:17], v[16:17], v[166:167], v[40:41]
	global_store_dwordx4 v[32:33], v[16:19], off offset:512
	s_waitcnt vmcnt(5)
	v_pk_fma_f32 v[10:11], v[10:11], v[168:169], v[46:47]
	v_pk_fma_f32 v[8:9], v[8:9], v[170:171], v[44:45]
	v_lshl_add_u64 v[16:17], s[12:13], 0, v[66:67]
	global_store_dwordx4 v[32:33], v[8:11], off offset:576
	v_lshl_add_u64 v[16:17], v[16:17], 0, v[172:173]
	v_pk_fma_f32 v[30:31], v[30:31], v[156:157], v[34:35]
	s_waitcnt vmcnt(5)
	v_pk_fma_f32 v[10:11], v[22:23], v[156:157], v[50:51]
	v_pk_fma_f32 v[8:9], v[20:21], v[158:159], v[48:49]
	v_pk_fma_f32 v[26:27], v[26:27], v[160:161], v[38:39]
	v_pk_fma_f32 v[24:25], v[24:25], v[162:163], v[36:37]
	global_store_dwordx4 v[16:17], v[8:11], off
	s_waitcnt vmcnt(4)
	v_pk_fma_f32 v[6:7], v[6:7], v[164:165], v[58:59]
	v_pk_fma_f32 v[4:5], v[4:5], v[166:167], v[56:57]
	v_pk_fma_f32 v[10:11], v[14:15], v[160:161], v[54:55]
	v_pk_fma_f32 v[8:9], v[12:13], v[162:163], v[52:53]
	s_waitcnt vmcnt(3)
	v_pk_fma_f32 v[2:3], v[2:3], v[168:169], v[62:63]
	v_pk_fma_f32 v[0:1], v[0:1], v[170:171], v[60:61]
	global_store_dwordx4 v[32:33], v[28:31], off
	global_store_dwordx4 v[32:33], v[24:27], off offset:64
	global_store_dwordx4 v[16:17], v[8:11], off offset:64
	global_store_dwordx4 v[16:17], v[4:7], off offset:512
	global_store_dwordx4 v[16:17], v[0:3], off offset:576
	s_waitcnt vmcnt(0)
	s_barrier
	s_and_saveexec_b64 s[36:37], s[4:5]
	s_cbranch_execz .LBB0_1498
	s_lshl_b32 s38, s67, 2
	s_ashr_i32 s39, s38, 31
	s_lshl_b64 s[38:39], s[38:39], 2
	s_add_u32 s38, s55, s38
	s_addc_u32 s39, s56, s39
	s_getreg_b32 s40, hwreg(HW_REG_XCC_ID, 0, 4)
	global_load_dwordx4 v[0:3], v129, s[38:39]
	s_and_b32 s38, s40, 15
	s_add_i32 s38, s38, 1
	s_waitcnt vmcnt(0)
	v_cmp_ne_u32_e32 vcc, s38, v2
	s_nop 1
	v_cndmask_b32_e64 v2, 0, 1, vcc
	v_cmp_ne_u32_e32 vcc, s38, v3
	v_lshlrev_b32_e32 v2, 2, v2
	s_nop 0
	v_cndmask_b32_e64 v3, 0, 1, vcc
	v_cmp_ne_u32_e32 vcc, s38, v1
	v_lshlrev_b32_e32 v3, 3, v3
	v_or_b32_e32 v2, v3, v2
	v_cndmask_b32_e64 v1, 0, 1, vcc
	v_cmp_ne_u32_e32 vcc, s38, v0
	v_lshlrev_b32_e32 v1, 1, v1
	s_nop 0
	v_cndmask_b32_e64 v0, 0, 1, vcc
	v_or_b32_e32 v0, v0, v1
	v_and_b32_e32 v0, 3, v0
	v_or_b32_e32 v0, v0, v2
	v_and_b32_e32 v0, 15, v0
	v_cmp_eq_u32_e32 vcc, 0, v0
	s_cbranch_vccnz .LBB0_1487
	buffer_wbl2 sc1
	s_waitcnt vmcnt(0)

.LBB0_1648:
	v_lshl_or_b32 v172, s74, 8, v198
	v_add_u32_e32 v156, 0x800, v172
	v_ashrrev_i32_e32 v157, 31, v156
	s_ashr_i32 s48, s44, 3
	v_lshlrev_b64 v[160:161], 2, v[156:157]
	s_add_i32 s49, s48, 64
	v_lshl_add_u64 v[164:165], s[14:15], 0, v[160:161]
	v_lshl_add_u64 v[156:157], s[18:19], 0, v[160:161]
	v_mad_i64_i32 v[160:161], s[36:37], s49, v211, v[164:165]
	global_load_dwordx4 v[156:159], v[156:157], off
	s_add_i32 s47, s48, 0x48
	s_add_i32 s46, s48, 0x50
	s_add_i32 s45, s48, 0x58
	s_add_i32 s79, s48, 0x60
	s_add_i32 s78, s48, 0x68
	s_add_i32 s77, s48, 0x70
	s_add_i32 s76, s48, 0x78
	s_lshl_b32 s75, s44, 8
	global_load_dwordx4 v[160:163], v[160:161], off
	v_mad_i64_i32 v[212:213], s[36:37], s47, v211, v[164:165]
	global_load_dwordx4 v[212:215], v[212:213], off
	v_mad_i64_i32 v[216:217], s[36:37], s46, v211, v[164:165]
	global_load_dwordx4 v[216:219], v[216:217], off
	v_mad_i64_i32 v[220:221], s[36:37], s45, v211, v[164:165]
	global_load_dwordx4 v[220:223], v[220:221], off
	v_mad_i64_i32 v[224:225], s[36:37], s79, v211, v[164:165]
	global_load_dwordx4 v[224:227], v[224:225], off
	v_mad_i64_i32 v[228:229], s[36:37], s78, v211, v[164:165]
	global_load_dwordx4 v[228:231], v[228:229], off
	v_mad_i64_i32 v[232:233], s[36:37], s77, v211, v[164:165]
	global_load_dwordx4 v[232:235], v[232:233], off
	v_mad_i64_i32 v[236:237], s[36:37], s76, v211, v[164:165]
	global_load_dwordx4 v[236:239], v[236:237], off
	v_ashrrev_i32_e32 v173, 31, v172
	v_readfirstlane_b32 s80, v180
	s_waitcnt vmcnt(7)
	v_pk_add_f32 v[160:161], v[156:157], v[160:161]
	v_pk_add_f32 v[162:163], v[158:159], v[162:163]
	s_waitcnt vmcnt(6)
	v_pk_add_f32 v[160:161], v[160:161], v[212:213]
	v_pk_add_f32 v[162:163], v[162:163], v[214:215]
	s_waitcnt vmcnt(5)
	v_pk_add_f32 v[160:161], v[160:161], v[216:217]
	v_pk_add_f32 v[162:163], v[162:163], v[218:219]
	s_waitcnt vmcnt(4)
	v_pk_add_f32 v[160:161], v[160:161], v[220:221]
	v_pk_add_f32 v[162:163], v[162:163], v[222:223]
	s_waitcnt vmcnt(3)
	v_pk_add_f32 v[160:161], v[160:161], v[224:225]
	v_pk_add_f32 v[162:163], v[162:163], v[226:227]
	s_waitcnt vmcnt(2)
	v_pk_add_f32 v[160:161], v[160:161], v[228:229]
	v_pk_add_f32 v[162:163], v[162:163], v[230:231]
	s_waitcnt vmcnt(1)
	v_pk_add_f32 v[160:161], v[160:161], v[232:233]
	v_pk_add_f32 v[162:163], v[162:163], v[234:235]
	s_waitcnt vmcnt(0)
	v_pk_add_f32 v[158:159], v[162:163], v[238:239]
	v_pk_add_f32 v[160:161], v[160:161], v[236:237]
	v_pk_mul_f32 v[156:157], v[158:159], 0.5 op_sel_hi:[1, 0]
	v_pk_mul_f32 v[158:159], v[160:161], 0.5 op_sel_hi:[1, 0]
	v_add_u32_e32 v160, 0x810, v172
	v_ashrrev_i32_e32 v161, 31, v160
	v_lshlrev_b64 v[164:165], 2, v[160:161]
	v_lshl_add_u64 v[168:169], s[14:15], 0, v[164:165]
	v_lshl_add_u64 v[160:161], s[18:19], 0, v[164:165]
	v_mad_i64_i32 v[164:165], s[36:37], s49, v211, v[168:169]
	global_load_dwordx4 v[160:163], v[160:161], off
	global_load_dwordx4 v[164:167], v[164:165], off
	v_mad_i64_i32 v[212:213], s[36:37], s47, v211, v[168:169]
	global_load_dwordx4 v[212:215], v[212:213], off
	v_mad_i64_i32 v[216:217], s[36:37], s46, v211, v[168:169]
	global_load_dwordx4 v[216:219], v[216:217], off
	v_mad_i64_i32 v[220:221], s[36:37], s45, v211, v[168:169]
	global_load_dwordx4 v[220:223], v[220:221], off
	v_mad_i64_i32 v[224:225], s[36:37], s79, v211, v[168:169]
	global_load_dwordx4 v[224:227], v[224:225], off
	v_mad_i64_i32 v[228:229], s[36:37], s78, v211, v[168:169]
	global_load_dwordx4 v[228:231], v[228:229], off
	v_mad_i64_i32 v[232:233], s[36:37], s77, v211, v[168:169]
	global_load_dwordx4 v[232:235], v[232:233], off
	v_mad_i64_i32 v[236:237], s[36:37], s76, v211, v[168:169]
	global_load_dwordx4 v[236:239], v[236:237], off
	s_waitcnt vmcnt(7)
	v_pk_add_f32 v[164:165], v[160:161], v[164:165]
	v_pk_add_f32 v[166:167], v[162:163], v[166:167]
	s_waitcnt vmcnt(6)
	v_pk_add_f32 v[164:165], v[164:165], v[212:213]
	v_pk_add_f32 v[166:167], v[166:167], v[214:215]
	s_waitcnt vmcnt(5)
	v_pk_add_f32 v[164:165], v[164:165], v[216:217]
	v_pk_add_f32 v[166:167], v[166:167], v[218:219]
	s_waitcnt vmcnt(4)
	v_pk_add_f32 v[164:165], v[164:165], v[220:221]
	v_pk_add_f32 v[166:167], v[166:167], v[222:223]
	s_waitcnt vmcnt(3)
	v_pk_add_f32 v[164:165], v[164:165], v[224:225]
	v_pk_add_f32 v[166:167], v[166:167], v[226:227]
	s_waitcnt vmcnt(2)
	v_pk_add_f32 v[164:165], v[164:165], v[228:229]
	v_pk_add_f32 v[166:167], v[166:167], v[230:231]
	s_waitcnt vmcnt(1)
	v_pk_add_f32 v[164:165], v[164:165], v[232:233]
	v_pk_add_f32 v[166:167], v[166:167], v[234:235]
	s_waitcnt vmcnt(0)
	v_pk_add_f32 v[162:163], v[166:167], v[238:239]
	v_pk_add_f32 v[164:165], v[164:165], v[236:237]
	v_pk_mul_f32 v[160:161], v[162:163], 0.5 op_sel_hi:[1, 0]
	v_pk_mul_f32 v[162:163], v[164:165], 0.5 op_sel_hi:[1, 0]
	v_add_u32_e32 v164, 0x880, v172
	v_ashrrev_i32_e32 v165, 31, v164
	v_lshlrev_b64 v[168:169], 2, v[164:165]
	v_lshl_add_u64 v[174:175], s[14:15], 0, v[168:169]
	v_lshl_add_u64 v[164:165], s[18:19], 0, v[168:169]
	v_mad_i64_i32 v[168:169], s[36:37], s49, v211, v[174:175]
	global_load_dwordx4 v[164:167], v[164:165], off
	global_load_dwordx4 v[168:171], v[168:169], off
	v_mad_i64_i32 v[212:213], s[36:37], s47, v211, v[174:175]
	global_load_dwordx4 v[212:215], v[212:213], off
	v_mad_i64_i32 v[216:217], s[36:37], s46, v211, v[174:175]
	global_load_dwordx4 v[216:219], v[216:217], off
	v_mad_i64_i32 v[220:221], s[36:37], s45, v211, v[174:175]
	global_load_dwordx4 v[220:223], v[220:221], off
	v_mad_i64_i32 v[224:225], s[36:37], s79, v211, v[174:175]
	global_load_dwordx4 v[224:227], v[224:225], off
	v_mad_i64_i32 v[228:229], s[36:37], s78, v211, v[174:175]
	global_load_dwordx4 v[228:231], v[228:229], off
	v_mad_i64_i32 v[232:233], s[36:37], s77, v211, v[174:175]
	global_load_dwordx4 v[232:235], v[232:233], off
	v_mad_i64_i32 v[236:237], s[36:37], s76, v211, v[174:175]
	global_load_dwordx4 v[236:239], v[236:237], off
	s_waitcnt vmcnt(7)
	v_pk_add_f32 v[168:169], v[164:165], v[168:169]
	v_pk_add_f32 v[170:171], v[166:167], v[170:171]
	s_waitcnt vmcnt(6)
	v_pk_add_f32 v[168:169], v[168:169], v[212:213]
	v_pk_add_f32 v[170:171], v[170:171], v[214:215]
	s_waitcnt vmcnt(5)
	v_pk_add_f32 v[168:169], v[168:169], v[216:217]
	v_pk_add_f32 v[170:171], v[170:171], v[218:219]
	s_waitcnt vmcnt(4)
	v_pk_add_f32 v[168:169], v[168:169], v[220:221]
	v_pk_add_f32 v[170:171], v[170:171], v[222:223]
	s_waitcnt vmcnt(3)
	v_pk_add_f32 v[168:169], v[168:169], v[224:225]
	v_pk_add_f32 v[170:171], v[170:171], v[226:227]
	s_waitcnt vmcnt(2)
	v_pk_add_f32 v[168:169], v[168:169], v[228:229]
	v_pk_add_f32 v[170:171], v[170:171], v[230:231]
	s_waitcnt vmcnt(1)
	v_pk_add_f32 v[168:169], v[168:169], v[232:233]
	v_pk_add_f32 v[170:171], v[170:171], v[234:235]
	s_waitcnt vmcnt(0)
	v_pk_add_f32 v[166:167], v[170:171], v[238:239]
	v_pk_add_f32 v[168:169], v[168:169], v[236:237]
	v_pk_mul_f32 v[164:165], v[166:167], 0.5 op_sel_hi:[1, 0]
	v_pk_mul_f32 v[166:167], v[168:169], 0.5 op_sel_hi:[1, 0]
	v_add_u32_e32 v168, 0x890, v172
	v_ashrrev_i32_e32 v169, 31, v168
	v_lshlrev_b64 v[174:175], 2, v[168:169]
	v_lshl_add_u64 v[178:179], s[14:15], 0, v[174:175]
	v_lshl_add_u64 v[168:169], s[18:19], 0, v[174:175]
	v_mad_i64_i32 v[174:175], s[36:37], s49, v211, v[178:179]
	global_load_dwordx4 v[168:171], v[168:169], off
	global_load_dwordx4 v[174:177], v[174:175], off
	v_mad_i64_i32 v[212:213], s[36:37], s47, v211, v[178:179]
	global_load_dwordx4 v[212:215], v[212:213], off
	v_mad_i64_i32 v[216:217], s[36:37], s46, v211, v[178:179]
	global_load_dwordx4 v[216:219], v[216:217], off
	v_mad_i64_i32 v[220:221], s[36:37], s45, v211, v[178:179]
	global_load_dwordx4 v[220:223], v[220:221], off
	v_mad_i64_i32 v[224:225], s[36:37], s79, v211, v[178:179]
	global_load_dwordx4 v[224:227], v[224:225], off
	v_mad_i64_i32 v[228:229], s[36:37], s78, v211, v[178:179]
	global_load_dwordx4 v[228:231], v[228:229], off
	v_mad_i64_i32 v[232:233], s[36:37], s77, v211, v[178:179]
	global_load_dwordx4 v[232:235], v[232:233], off
	v_mad_i64_i32 v[236:237], s[36:37], s76, v211, v[178:179]
	global_load_dwordx4 v[236:239], v[236:237], off
	v_lshlrev_b64 v[172:173], 2, v[172:173]
	s_waitcnt vmcnt(7)
	v_pk_add_f32 v[174:175], v[168:169], v[174:175]
	v_pk_add_f32 v[176:177], v[170:171], v[176:177]
	s_waitcnt vmcnt(6)
	v_pk_add_f32 v[174:175], v[174:175], v[212:213]
	v_pk_add_f32 v[176:177], v[176:177], v[214:215]
	s_waitcnt vmcnt(5)
	v_pk_add_f32 v[174:175], v[174:175], v[216:217]
	v_pk_add_f32 v[176:177], v[176:177], v[218:219]
	s_waitcnt vmcnt(4)
	v_pk_add_f32 v[174:175], v[174:175], v[220:221]
	v_pk_add_f32 v[176:177], v[176:177], v[222:223]
	s_waitcnt vmcnt(3)
	v_pk_add_f32 v[174:175], v[174:175], v[224:225]
	v_pk_add_f32 v[176:177], v[176:177], v[226:227]
	s_waitcnt vmcnt(2)
	v_pk_add_f32 v[174:175], v[174:175], v[228:229]
	v_pk_add_f32 v[176:177], v[176:177], v[230:231]
	s_waitcnt vmcnt(1)
	v_pk_add_f32 v[174:175], v[174:175], v[232:233]
	v_pk_add_f32 v[176:177], v[176:177], v[234:235]
	v_add_u32_e32 v178, s75, v181
	v_ashrrev_i32_e32 v179, 31, v178
	s_waitcnt vmcnt(0)
	v_pk_add_f32 v[170:171], v[176:177], v[238:239]
	v_pk_add_f32 v[174:175], v[174:175], v[236:237]
	v_pk_mul_f32 v[168:169], v[170:171], 0.5 op_sel_hi:[1, 0]
	v_pk_mul_f32 v[170:171], v[174:175], 0.5 op_sel_hi:[1, 0]
	v_lshl_add_u64 v[174:175], s[12:13], 0, v[172:173]
	v_lshlrev_b64 v[176:177], 12, v[178:179]
	v_lshl_add_u64 v[204:205], v[174:175], 0, v[176:177]
	global_load_dwordx4 v[212:215], v[204:205], off
	global_load_dwordx4 v[216:219], v[204:205], off offset:64
	global_load_dwordx4 v[220:223], v[204:205], off offset:512
	global_load_dwordx4 v[224:227], v[204:205], off offset:576
	v_or_b32_e32 v204, 16, v178
	v_ashrrev_i32_e32 v205, 31, v204
	v_lshlrev_b64 v[204:205], 12, v[204:205]
	v_lshl_add_u64 v[206:207], v[174:175], 0, v[204:205]
	global_load_dwordx4 v[228:231], v[206:207], off
	global_load_dwordx4 v[232:235], v[206:207], off offset:64
	global_load_dwordx4 v[236:239], v[206:207], off offset:512
	global_load_dwordx4 v[240:243], v[206:207], off offset:576
	v_lshl_add_u64 v[206:207], s[12:13], 0, v[176:177]
	v_lshl_add_u64 v[206:207], v[206:207], 0, v[172:173]
	s_waitcnt vmcnt(7)
	v_pk_fma_f32 v[126:127], v[126:127], v[156:157], v[214:215]
	v_pk_fma_f32 v[124:125], v[124:125], v[158:159], v[212:213]
	s_waitcnt vmcnt(5)
	v_pk_fma_f32 v[110:111], v[110:111], v[164:165], v[222:223]
	v_pk_fma_f32 v[108:109], v[108:109], v[166:167], v[220:221]
	global_store_dwordx4 v[206:207], v[108:111], off offset:512
	s_waitcnt vmcnt(5)
	v_pk_fma_f32 v[106:107], v[106:107], v[168:169], v[226:227]
	v_pk_fma_f32 v[104:105], v[104:105], v[170:171], v[224:225]
	v_lshl_add_u64 v[108:109], s[12:13], 0, v[204:205]
	v_lshl_add_u64 v[108:109], v[108:109], 0, v[172:173]
	s_waitcnt vmcnt(1)
	v_pk_fma_f32 v[98:99], v[98:99], v[168:169], v[242:243]
	v_pk_fma_f32 v[96:97], v[96:97], v[170:171], v[240:241]
	global_store_dwordx4 v[108:109], v[96:99], off offset:576
	global_store_dwordx4 v[206:207], v[104:107], off offset:576
	v_pk_fma_f32 v[122:123], v[122:123], v[160:161], v[218:219]
	v_or_b32_e32 v96, 32, v178
	v_pk_fma_f32 v[106:107], v[118:119], v[156:157], v[230:231]
	v_pk_fma_f32 v[104:105], v[116:117], v[158:159], v[228:229]
	v_ashrrev_i32_e32 v97, 31, v96
	v_pk_fma_f32 v[120:121], v[120:121], v[162:163], v[216:217]
	global_store_dwordx4 v[108:109], v[104:107], off
	v_pk_fma_f32 v[102:103], v[102:103], v[164:165], v[238:239]
	v_pk_fma_f32 v[100:101], v[100:101], v[166:167], v[236:237]
	v_pk_fma_f32 v[106:107], v[114:115], v[160:161], v[234:235]
	v_pk_fma_f32 v[104:105], v[112:113], v[162:163], v[232:233]
	v_lshlrev_b64 v[204:205], 12, v[96:97]
	v_or_b32_e32 v112, 48, v178
	global_store_dwordx4 v[206:207], v[124:127], off
	global_store_dwordx4 v[206:207], v[120:123], off offset:64
	global_store_dwordx4 v[108:109], v[104:107], off offset:64
	global_store_dwordx4 v[108:109], v[100:103], off offset:512
	v_lshl_add_u64 v[108:109], v[174:175], 0, v[204:205]
	v_ashrrev_i32_e32 v113, 31, v112
	global_load_dwordx4 v[96:99], v[108:109], off
	global_load_dwordx4 v[100:103], v[108:109], off offset:64
	global_load_dwordx4 v[104:107], v[108:109], off offset:512
	s_nop 0
	global_load_dwordx4 v[108:111], v[108:109], off offset:576
	v_lshlrev_b64 v[178:179], 12, v[112:113]
	v_lshl_add_u64 v[124:125], v[174:175], 0, v[178:179]
	global_load_dwordx4 v[112:115], v[124:125], off
	global_load_dwordx4 v[116:119], v[124:125], off offset:64
	global_load_dwordx4 v[120:123], v[124:125], off offset:512
	s_nop 0
	global_load_dwordx4 v[124:127], v[124:125], off offset:576
	s_waitcnt vmcnt(7)
	v_pk_fma_f32 v[92:93], v[92:93], v[158:159], v[96:97]
	v_lshl_add_u64 v[96:97], s[12:13], 0, v[204:205]
	v_lshl_add_u64 v[96:97], v[96:97], 0, v[172:173]
	s_waitcnt vmcnt(5)
	v_pk_fma_f32 v[78:79], v[78:79], v[164:165], v[106:107]
	v_pk_fma_f32 v[76:77], v[76:77], v[166:167], v[104:105]
	global_store_dwordx4 v[96:97], v[76:79], off offset:512
	s_waitcnt vmcnt(5)
	v_pk_fma_f32 v[74:75], v[74:75], v[168:169], v[110:111]
	v_pk_fma_f32 v[72:73], v[72:73], v[170:171], v[108:109]
	v_lshl_add_u64 v[76:77], s[12:13], 0, v[178:179]
	v_pk_fma_f32 v[94:95], v[94:95], v[156:157], v[98:99]
	v_pk_fma_f32 v[90:91], v[90:91], v[160:161], v[102:103]
	v_pk_fma_f32 v[88:89], v[88:89], v[162:163], v[100:101]
	global_store_dwordx4 v[96:97], v[72:75], off offset:576
	v_lshl_add_u64 v[76:77], v[76:77], 0, v[172:173]
	global_store_dwordx4 v[96:97], v[92:95], off
	s_waitcnt vmcnt(6)
	v_pk_fma_f32 v[74:75], v[86:87], v[156:157], v[114:115]
	v_pk_fma_f32 v[72:73], v[84:85], v[158:159], v[112:113]
	global_store_dwordx4 v[96:97], v[88:91], off offset:64
	global_store_dwordx4 v[76:77], v[72:75], off
	s_waitcnt vmcnt(6)
	v_pk_fma_f32 v[70:71], v[70:71], v[164:165], v[122:123]
	v_pk_fma_f32 v[68:69], v[68:69], v[166:167], v[120:121]
	v_pk_fma_f32 v[74:75], v[82:83], v[160:161], v[118:119]
	v_pk_fma_f32 v[72:73], v[80:81], v[162:163], v[116:117]
	s_waitcnt vmcnt(5)
	v_pk_fma_f32 v[66:67], v[66:67], v[168:169], v[126:127]
	v_pk_fma_f32 v[64:65], v[64:65], v[170:171], v[124:125]
	v_lshl_add_u64 v[96:97], v[176:177], 0, s[20:21]
	global_store_dwordx4 v[76:77], v[72:75], off offset:64
	global_store_dwordx4 v[76:77], v[68:71], off offset:512
	global_store_dwordx4 v[76:77], v[64:67], off offset:576
	v_lshl_add_u64 v[76:77], v[174:175], 0, v[96:97]
	global_load_dwordx4 v[64:67], v[76:77], off
	global_load_dwordx4 v[68:71], v[76:77], off offset:64
	global_load_dwordx4 v[72:75], v[76:77], off offset:512
	s_nop 0
	global_load_dwordx4 v[76:79], v[76:77], off offset:576
	v_lshl_add_u64 v[98:99], v[176:177], 0, s[22:23]
	v_lshl_add_u64 v[92:93], v[174:175], 0, v[98:99]
	global_load_dwordx4 v[80:83], v[92:93], off
	global_load_dwordx4 v[84:87], v[92:93], off offset:64
	global_load_dwordx4 v[88:91], v[92:93], off offset:512
	s_nop 0
	global_load_dwordx4 v[92:95], v[92:93], off offset:576
	s_waitcnt vmcnt(7)
	v_pk_fma_f32 v[60:61], v[60:61], v[158:159], v[64:65]
	v_lshl_add_u64 v[64:65], s[12:13], 0, v[96:97]
	v_lshl_add_u64 v[64:65], v[64:65], 0, v[172:173]
	s_waitcnt vmcnt(5)
	v_pk_fma_f32 v[46:47], v[46:47], v[164:165], v[74:75]
	v_pk_fma_f32 v[44:45], v[44:45], v[166:167], v[72:73]
	global_store_dwordx4 v[64:65], v[44:47], off offset:512
	s_waitcnt vmcnt(5)
	v_pk_fma_f32 v[42:43], v[42:43], v[168:169], v[78:79]
	v_pk_fma_f32 v[40:41], v[40:41], v[170:171], v[76:77]
	v_lshl_add_u64 v[44:45], s[12:13], 0, v[98:99]
	v_pk_fma_f32 v[62:63], v[62:63], v[156:157], v[66:67]
	v_pk_fma_f32 v[58:59], v[58:59], v[160:161], v[70:71]
	v_pk_fma_f32 v[56:57], v[56:57], v[162:163], v[68:69]
	global_store_dwordx4 v[64:65], v[40:43], off offset:576
	v_lshl_add_u64 v[44:45], v[44:45], 0, v[172:173]
	global_store_dwordx4 v[64:65], v[60:63], off
	s_waitcnt vmcnt(6)
	v_pk_fma_f32 v[42:43], v[54:55], v[156:157], v[82:83]
	v_pk_fma_f32 v[40:41], v[52:53], v[158:159], v[80:81]
	global_store_dwordx4 v[64:65], v[56:59], off offset:64
	global_store_dwordx4 v[44:45], v[40:43], off
	s_waitcnt vmcnt(6)
	v_pk_fma_f32 v[38:39], v[38:39], v[164:165], v[90:91]
	v_pk_fma_f32 v[36:37], v[36:37], v[166:167], v[88:89]
	v_pk_fma_f32 v[42:43], v[50:51], v[160:161], v[86:87]
	v_pk_fma_f32 v[40:41], v[48:49], v[162:163], v[84:85]
	s_waitcnt vmcnt(5)
	v_pk_fma_f32 v[34:35], v[34:35], v[168:169], v[94:95]
	v_pk_fma_f32 v[32:33], v[32:33], v[170:171], v[92:93]
	v_lshl_add_u64 v[64:65], v[176:177], 0, s[24:25]
	global_store_dwordx4 v[44:45], v[40:43], off offset:64
	global_store_dwordx4 v[44:45], v[36:39], off offset:512
	global_store_dwordx4 v[44:45], v[32:35], off offset:576
	v_lshl_add_u64 v[44:45], v[174:175], 0, v[64:65]
	global_load_dwordx4 v[32:35], v[44:45], off
	global_load_dwordx4 v[36:39], v[44:45], off offset:64
	global_load_dwordx4 v[40:43], v[44:45], off offset:512
	s_nop 0
	global_load_dwordx4 v[44:47], v[44:45], off offset:576
	v_lshl_add_u64 v[66:67], v[176:177], 0, s[26:27]
	v_lshl_add_u64 v[60:61], v[174:175], 0, v[66:67]
	global_load_dwordx4 v[48:51], v[60:61], off
	global_load_dwordx4 v[52:55], v[60:61], off offset:64
	global_load_dwordx4 v[56:59], v[60:61], off offset:512
	s_nop 0
	global_load_dwordx4 v[60:63], v[60:61], off offset:576
	s_waitcnt vmcnt(7)
	v_pk_fma_f32 v[28:29], v[28:29], v[158:159], v[32:33]
	v_lshl_add_u64 v[32:33], s[12:13], 0, v[64:65]
	v_lshl_add_u64 v[32:33], v[32:33], 0, v[172:173]
	s_waitcnt vmcnt(5)
	v_pk_fma_f32 v[18:19], v[18:19], v[164:165], v[42:43]
	v_pk_fma_f32 v[16:17], v[16:17], v[166:167], v[40:41]
	global_store_dwordx4 v[32:33], v[16:19], off offset:512
	s_waitcnt vmcnt(5)
	v_pk_fma_f32 v[10:11], v[10:11], v[168:169], v[46:47]
	v_pk_fma_f32 v[8:9], v[8:9], v[170:171], v[44:45]
	v_lshl_add_u64 v[16:17], s[12:13], 0, v[66:67]
	global_store_dwordx4 v[32:33], v[8:11], off offset:576
	v_lshl_add_u64 v[16:17], v[16:17], 0, v[172:173]
	v_pk_fma_f32 v[30:31], v[30:31], v[156:157], v[34:35]
	s_waitcnt vmcnt(5)
	v_pk_fma_f32 v[10:11], v[22:23], v[156:157], v[50:51]
	v_pk_fma_f32 v[8:9], v[20:21], v[158:159], v[48:49]
	v_pk_fma_f32 v[26:27], v[26:27], v[160:161], v[38:39]
	v_pk_fma_f32 v[24:25], v[24:25], v[162:163], v[36:37]
	global_store_dwordx4 v[16:17], v[8:11], off
	s_waitcnt vmcnt(4)
	v_pk_fma_f32 v[6:7], v[6:7], v[164:165], v[58:59]
	v_pk_fma_f32 v[4:5], v[4:5], v[166:167], v[56:57]
	v_pk_fma_f32 v[10:11], v[14:15], v[160:161], v[54:55]
	v_pk_fma_f32 v[8:9], v[12:13], v[162:163], v[52:53]
	s_waitcnt vmcnt(3)
	v_pk_fma_f32 v[2:3], v[2:3], v[168:169], v[62:63]
	v_pk_fma_f32 v[0:1], v[0:1], v[170:171], v[60:61]
	global_store_dwordx4 v[32:33], v[28:31], off
	global_store_dwordx4 v[32:33], v[24:27], off offset:64
	global_store_dwordx4 v[16:17], v[8:11], off offset:64
	global_store_dwordx4 v[16:17], v[4:7], off offset:512
	global_store_dwordx4 v[16:17], v[0:3], off offset:576
	s_waitcnt vmcnt(0)
	s_barrier
	s_and_saveexec_b64 s[36:37], s[4:5]
	s_cbranch_execz .LBB0_1662
	s_lshl_b32 s38, s44, 2
	s_ashr_i32 s39, s38, 31
	s_lshl_b64 s[38:39], s[38:39], 2
	s_add_u32 s38, s63, s38
	s_addc_u32 s39, s64, s39
	s_getreg_b32 s40, hwreg(HW_REG_XCC_ID, 0, 4)
	global_load_dwordx4 v[0:3], v129, s[38:39]
	s_and_b32 s38, s40, 15
	s_add_i32 s38, s38, 1
	s_waitcnt vmcnt(0)
	v_cmp_ne_u32_e32 vcc, s38, v2
	s_nop 1
	v_cndmask_b32_e64 v2, 0, 1, vcc
	v_cmp_ne_u32_e32 vcc, s38, v3
	v_lshlrev_b32_e32 v2, 2, v2
	s_nop 0
	v_cndmask_b32_e64 v3, 0, 1, vcc
	v_cmp_ne_u32_e32 vcc, s38, v1
	v_lshlrev_b32_e32 v3, 3, v3
	v_or_b32_e32 v2, v3, v2
	v_cndmask_b32_e64 v1, 0, 1, vcc
	v_cmp_ne_u32_e32 vcc, s38, v0
	v_lshlrev_b32_e32 v1, 1, v1
	s_nop 0
	v_cndmask_b32_e64 v0, 0, 1, vcc
	v_or_b32_e32 v0, v0, v1
	v_and_b32_e32 v0, 3, v0
	v_or_b32_e32 v0, v0, v2
	v_and_b32_e32 v0, 15, v0
	v_cmp_eq_u32_e32 vcc, 0, v0
	s_cbranch_vccnz .LBB0_1651
	buffer_wbl2 sc1
	s_waitcnt vmcnt(0)

.LBB0_2361:
	v_lshl_or_b32 v172, s42, 8, v198
	v_add_u32_e32 v156, 0x1400, v172
	v_ashrrev_i32_e32 v157, 31, v156
	s_ashr_i32 s55, s44, 3
	v_lshlrev_b64 v[160:161], 2, v[156:157]
	s_add_i32 s56, s55, 64
	v_lshl_add_u64 v[164:165], s[2:3], 0, v[160:161]
	v_lshl_add_u64 v[156:157], s[18:19], 0, v[160:161]
	v_mad_i64_i32 v[160:161], s[46:47], s56, v211, v[164:165]
	global_load_dwordx4 v[156:159], v[156:157], off
	s_add_i32 s54, s55, 0x48
	s_add_i32 s53, s55, 0x50
	s_add_i32 s52, s55, 0x58
	s_add_i32 s81, s55, 0x60
	s_add_i32 s80, s55, 0x68
	s_add_i32 s43, s55, 0x70
	s_add_i32 s37, s55, 0x78
	s_lshl_b32 s35, s44, 8
	global_load_dwordx4 v[160:163], v[160:161], off
	v_mad_i64_i32 v[212:213], s[46:47], s54, v211, v[164:165]
	global_load_dwordx4 v[212:215], v[212:213], off
	v_mad_i64_i32 v[216:217], s[46:47], s53, v211, v[164:165]
	global_load_dwordx4 v[216:219], v[216:217], off
	v_mad_i64_i32 v[220:221], s[46:47], s52, v211, v[164:165]
	global_load_dwordx4 v[220:223], v[220:221], off
	v_mad_i64_i32 v[224:225], s[46:47], s81, v211, v[164:165]
	global_load_dwordx4 v[224:227], v[224:225], off
	v_mad_i64_i32 v[228:229], s[46:47], s80, v211, v[164:165]
	global_load_dwordx4 v[228:231], v[228:229], off
	v_mad_i64_i32 v[232:233], s[46:47], s43, v211, v[164:165]
	global_load_dwordx4 v[232:235], v[232:233], off
	v_mad_i64_i32 v[236:237], s[46:47], s37, v211, v[164:165]
	global_load_dwordx4 v[236:239], v[236:237], off
	v_ashrrev_i32_e32 v173, 31, v172
	v_readfirstlane_b32 s82, v180
	s_waitcnt vmcnt(7)
	v_pk_add_f32 v[160:161], v[156:157], v[160:161]
	v_pk_add_f32 v[162:163], v[158:159], v[162:163]
	s_waitcnt vmcnt(6)
	v_pk_add_f32 v[160:161], v[160:161], v[212:213]
	v_pk_add_f32 v[162:163], v[162:163], v[214:215]
	s_waitcnt vmcnt(5)
	v_pk_add_f32 v[160:161], v[160:161], v[216:217]
	v_pk_add_f32 v[162:163], v[162:163], v[218:219]
	s_waitcnt vmcnt(4)
	v_pk_add_f32 v[160:161], v[160:161], v[220:221]
	v_pk_add_f32 v[162:163], v[162:163], v[222:223]
	s_waitcnt vmcnt(3)
	v_pk_add_f32 v[160:161], v[160:161], v[224:225]
	v_pk_add_f32 v[162:163], v[162:163], v[226:227]
	s_waitcnt vmcnt(2)
	v_pk_add_f32 v[160:161], v[160:161], v[228:229]
	v_pk_add_f32 v[162:163], v[162:163], v[230:231]
	s_waitcnt vmcnt(1)
	v_pk_add_f32 v[166:167], v[160:161], v[232:233]
	v_pk_add_f32 v[162:163], v[162:163], v[234:235]
	s_waitcnt vmcnt(0)
	v_pk_add_f32 v[156:157], v[162:163], v[238:239]
	v_add_u32_e32 v160, 0x1410, v172
	v_ashrrev_i32_e32 v161, 31, v160
	v_lshlrev_b64 v[164:165], 2, v[160:161]
	v_lshl_add_u64 v[168:169], s[2:3], 0, v[164:165]
	v_lshl_add_u64 v[160:161], s[18:19], 0, v[164:165]
	v_mad_i64_i32 v[164:165], s[46:47], s56, v211, v[168:169]
	v_pk_add_f32 v[158:159], v[166:167], v[236:237]
	global_load_dwordx4 v[160:163], v[160:161], off
	global_load_dwordx4 v[164:167], v[164:165], off
	v_mad_i64_i32 v[212:213], s[46:47], s54, v211, v[168:169]
	global_load_dwordx4 v[212:215], v[212:213], off
	v_mad_i64_i32 v[216:217], s[46:47], s53, v211, v[168:169]
	global_load_dwordx4 v[216:219], v[216:217], off
	v_mad_i64_i32 v[220:221], s[46:47], s52, v211, v[168:169]
	global_load_dwordx4 v[220:223], v[220:221], off
	v_mad_i64_i32 v[224:225], s[46:47], s81, v211, v[168:169]
	global_load_dwordx4 v[224:227], v[224:225], off
	v_mad_i64_i32 v[228:229], s[46:47], s80, v211, v[168:169]
	global_load_dwordx4 v[228:231], v[228:229], off
	v_mad_i64_i32 v[232:233], s[46:47], s43, v211, v[168:169]
	global_load_dwordx4 v[232:235], v[232:233], off
	v_mad_i64_i32 v[236:237], s[46:47], s37, v211, v[168:169]
	global_load_dwordx4 v[236:239], v[236:237], off
	s_waitcnt vmcnt(7)
	v_pk_add_f32 v[164:165], v[160:161], v[164:165]
	v_pk_add_f32 v[166:167], v[162:163], v[166:167]
	s_waitcnt vmcnt(6)
	v_pk_add_f32 v[164:165], v[164:165], v[212:213]
	v_pk_add_f32 v[166:167], v[166:167], v[214:215]
	s_waitcnt vmcnt(5)
	v_pk_add_f32 v[164:165], v[164:165], v[216:217]
	v_pk_add_f32 v[166:167], v[166:167], v[218:219]
	s_waitcnt vmcnt(4)
	v_pk_add_f32 v[164:165], v[164:165], v[220:221]
	v_pk_add_f32 v[166:167], v[166:167], v[222:223]
	s_waitcnt vmcnt(3)
	v_pk_add_f32 v[164:165], v[164:165], v[224:225]
	v_pk_add_f32 v[166:167], v[166:167], v[226:227]
	s_waitcnt vmcnt(2)
	v_pk_add_f32 v[164:165], v[164:165], v[228:229]
	v_pk_add_f32 v[166:167], v[166:167], v[230:231]
	s_waitcnt vmcnt(1)
	v_pk_add_f32 v[170:171], v[164:165], v[232:233]
	v_pk_add_f32 v[166:167], v[166:167], v[234:235]
	s_waitcnt vmcnt(0)
	v_pk_add_f32 v[160:161], v[166:167], v[238:239]
	v_add_u32_e32 v164, 0x1480, v172
	v_ashrrev_i32_e32 v165, 31, v164
	v_lshlrev_b64 v[168:169], 2, v[164:165]
	v_lshl_add_u64 v[174:175], s[2:3], 0, v[168:169]
	v_lshl_add_u64 v[164:165], s[18:19], 0, v[168:169]
	v_mad_i64_i32 v[168:169], s[46:47], s56, v211, v[174:175]
	v_pk_add_f32 v[162:163], v[170:171], v[236:237]
	global_load_dwordx4 v[164:167], v[164:165], off
	global_load_dwordx4 v[168:171], v[168:169], off
	v_mad_i64_i32 v[212:213], s[46:47], s54, v211, v[174:175]
	global_load_dwordx4 v[212:215], v[212:213], off
	v_mad_i64_i32 v[216:217], s[46:47], s53, v211, v[174:175]
	global_load_dwordx4 v[216:219], v[216:217], off
	v_mad_i64_i32 v[220:221], s[46:47], s52, v211, v[174:175]
	global_load_dwordx4 v[220:223], v[220:221], off
	v_mad_i64_i32 v[224:225], s[46:47], s81, v211, v[174:175]
	global_load_dwordx4 v[224:227], v[224:225], off
	v_mad_i64_i32 v[228:229], s[46:47], s80, v211, v[174:175]
	global_load_dwordx4 v[228:231], v[228:229], off
	v_mad_i64_i32 v[232:233], s[46:47], s43, v211, v[174:175]
	global_load_dwordx4 v[232:235], v[232:233], off
	v_mad_i64_i32 v[236:237], s[46:47], s37, v211, v[174:175]
	global_load_dwordx4 v[236:239], v[236:237], off
	s_waitcnt vmcnt(7)
	v_pk_add_f32 v[168:169], v[164:165], v[168:169]
	v_pk_add_f32 v[170:171], v[166:167], v[170:171]
	s_waitcnt vmcnt(6)
	v_pk_add_f32 v[168:169], v[168:169], v[212:213]
	v_pk_add_f32 v[170:171], v[170:171], v[214:215]
	s_waitcnt vmcnt(5)
	v_pk_add_f32 v[168:169], v[168:169], v[216:217]
	v_pk_add_f32 v[170:171], v[170:171], v[218:219]
	s_waitcnt vmcnt(4)
	v_pk_add_f32 v[168:169], v[168:169], v[220:221]
	v_pk_add_f32 v[170:171], v[170:171], v[222:223]
	s_waitcnt vmcnt(3)
	v_pk_add_f32 v[168:169], v[168:169], v[224:225]
	v_pk_add_f32 v[170:171], v[170:171], v[226:227]
	s_waitcnt vmcnt(2)
	v_pk_add_f32 v[168:169], v[168:169], v[228:229]
	v_pk_add_f32 v[170:171], v[170:171], v[230:231]
	s_waitcnt vmcnt(1)
	v_pk_add_f32 v[176:177], v[168:169], v[232:233]
	v_pk_add_f32 v[170:171], v[170:171], v[234:235]
	s_waitcnt vmcnt(0)
	v_pk_add_f32 v[164:165], v[170:171], v[238:239]
	v_add_u32_e32 v168, 0x1490, v172
	v_ashrrev_i32_e32 v169, 31, v168
	v_lshlrev_b64 v[174:175], 2, v[168:169]
	v_lshl_add_u64 v[178:179], s[2:3], 0, v[174:175]
	v_lshl_add_u64 v[168:169], s[18:19], 0, v[174:175]
	v_mad_i64_i32 v[174:175], s[46:47], s56, v211, v[178:179]
	v_pk_add_f32 v[166:167], v[176:177], v[236:237]
	global_load_dwordx4 v[168:171], v[168:169], off
	global_load_dwordx4 v[174:177], v[174:175], off
	v_mad_i64_i32 v[212:213], s[46:47], s54, v211, v[178:179]
	global_load_dwordx4 v[212:215], v[212:213], off
	v_mad_i64_i32 v[216:217], s[46:47], s53, v211, v[178:179]
	global_load_dwordx4 v[216:219], v[216:217], off
	v_mad_i64_i32 v[220:221], s[46:47], s52, v211, v[178:179]
	global_load_dwordx4 v[220:223], v[220:221], off
	v_mad_i64_i32 v[224:225], s[46:47], s81, v211, v[178:179]
	global_load_dwordx4 v[224:227], v[224:225], off
	v_mad_i64_i32 v[228:229], s[46:47], s80, v211, v[178:179]
	global_load_dwordx4 v[228:231], v[228:229], off
	v_mad_i64_i32 v[232:233], s[46:47], s43, v211, v[178:179]
	global_load_dwordx4 v[232:235], v[232:233], off
	v_mad_i64_i32 v[236:237], s[46:47], s37, v211, v[178:179]
	global_load_dwordx4 v[236:239], v[236:237], off
	v_lshlrev_b64 v[172:173], 2, v[172:173]
	s_waitcnt vmcnt(7)
	v_pk_add_f32 v[174:175], v[168:169], v[174:175]
	v_pk_add_f32 v[176:177], v[170:171], v[176:177]
	s_waitcnt vmcnt(6)
	v_pk_add_f32 v[174:175], v[174:175], v[212:213]
	v_pk_add_f32 v[176:177], v[176:177], v[214:215]
	s_waitcnt vmcnt(5)
	v_pk_add_f32 v[174:175], v[174:175], v[216:217]
	v_pk_add_f32 v[176:177], v[176:177], v[218:219]
	s_waitcnt vmcnt(4)
	v_pk_add_f32 v[174:175], v[174:175], v[220:221]
	v_pk_add_f32 v[176:177], v[176:177], v[222:223]
	s_waitcnt vmcnt(3)
	v_pk_add_f32 v[174:175], v[174:175], v[224:225]
	v_pk_add_f32 v[176:177], v[176:177], v[226:227]
	s_waitcnt vmcnt(2)
	v_pk_add_f32 v[174:175], v[174:175], v[228:229]
	v_pk_add_f32 v[176:177], v[176:177], v[230:231]
	s_waitcnt vmcnt(1)
	v_pk_add_f32 v[204:205], v[174:175], v[232:233]
	v_pk_add_f32 v[170:171], v[176:177], v[234:235]
	v_add_u32_e32 v178, s35, v181
	v_ashrrev_i32_e32 v179, 31, v178
	s_waitcnt vmcnt(0)
	v_pk_add_f32 v[168:169], v[170:171], v[238:239]
	v_pk_add_f32 v[170:171], v[204:205], v[236:237]
	v_lshl_add_u64 v[174:175], s[0:1], 0, v[172:173]
	v_lshlrev_b64 v[176:177], 12, v[178:179]
	v_lshl_add_u64 v[204:205], v[174:175], 0, v[176:177]
	global_load_dwordx4 v[212:215], v[204:205], off
	global_load_dwordx4 v[216:219], v[204:205], off offset:64
	global_load_dwordx4 v[220:223], v[204:205], off offset:512
	global_load_dwordx4 v[224:227], v[204:205], off offset:576
	v_or_b32_e32 v204, 16, v178
	v_ashrrev_i32_e32 v205, 31, v204
	v_lshlrev_b64 v[204:205], 12, v[204:205]
	v_lshl_add_u64 v[206:207], v[174:175], 0, v[204:205]
	global_load_dwordx4 v[228:231], v[206:207], off
	global_load_dwordx4 v[232:235], v[206:207], off offset:64
	global_load_dwordx4 v[236:239], v[206:207], off offset:512
	global_load_dwordx4 v[240:243], v[206:207], off offset:576
	v_lshl_add_u64 v[206:207], s[0:1], 0, v[176:177]
	v_lshl_add_u64 v[206:207], v[206:207], 0, v[172:173]
	s_waitcnt vmcnt(7)
	v_pk_fma_f32 v[126:127], v[126:127], v[156:157], v[214:215]
	v_pk_fma_f32 v[124:125], v[124:125], v[158:159], v[212:213]
	s_waitcnt vmcnt(5)
	v_pk_fma_f32 v[110:111], v[110:111], v[164:165], v[222:223]
	v_pk_fma_f32 v[108:109], v[108:109], v[166:167], v[220:221]
	global_store_dwordx4 v[206:207], v[108:111], off offset:512
	s_waitcnt vmcnt(5)
	v_pk_fma_f32 v[106:107], v[106:107], v[168:169], v[226:227]
	v_pk_fma_f32 v[104:105], v[104:105], v[170:171], v[224:225]
	v_lshl_add_u64 v[108:109], s[0:1], 0, v[204:205]
	v_lshl_add_u64 v[108:109], v[108:109], 0, v[172:173]
	s_waitcnt vmcnt(1)
	v_pk_fma_f32 v[98:99], v[98:99], v[168:169], v[242:243]
	v_pk_fma_f32 v[96:97], v[96:97], v[170:171], v[240:241]
	global_store_dwordx4 v[108:109], v[96:99], off offset:576
	global_store_dwordx4 v[206:207], v[104:107], off offset:576
	v_pk_fma_f32 v[122:123], v[122:123], v[160:161], v[218:219]
	v_or_b32_e32 v96, 32, v178
	v_pk_fma_f32 v[106:107], v[118:119], v[156:157], v[230:231]
	v_pk_fma_f32 v[104:105], v[116:117], v[158:159], v[228:229]
	v_ashrrev_i32_e32 v97, 31, v96
	v_pk_fma_f32 v[120:121], v[120:121], v[162:163], v[216:217]
	global_store_dwordx4 v[108:109], v[104:107], off
	v_pk_fma_f32 v[102:103], v[102:103], v[164:165], v[238:239]
	v_pk_fma_f32 v[100:101], v[100:101], v[166:167], v[236:237]
	v_pk_fma_f32 v[106:107], v[114:115], v[160:161], v[234:235]
	v_pk_fma_f32 v[104:105], v[112:113], v[162:163], v[232:233]
	v_lshlrev_b64 v[204:205], 12, v[96:97]
	v_or_b32_e32 v112, 48, v178
	global_store_dwordx4 v[206:207], v[124:127], off
	global_store_dwordx4 v[206:207], v[120:123], off offset:64
	global_store_dwordx4 v[108:109], v[104:107], off offset:64
	global_store_dwordx4 v[108:109], v[100:103], off offset:512
	v_lshl_add_u64 v[108:109], v[174:175], 0, v[204:205]
	v_ashrrev_i32_e32 v113, 31, v112
	global_load_dwordx4 v[96:99], v[108:109], off
	global_load_dwordx4 v[100:103], v[108:109], off offset:64
	global_load_dwordx4 v[104:107], v[108:109], off offset:512
	s_nop 0
	global_load_dwordx4 v[108:111], v[108:109], off offset:576
	v_lshlrev_b64 v[178:179], 12, v[112:113]
	v_lshl_add_u64 v[124:125], v[174:175], 0, v[178:179]
	global_load_dwordx4 v[112:115], v[124:125], off
	global_load_dwordx4 v[116:119], v[124:125], off offset:64
	global_load_dwordx4 v[120:123], v[124:125], off offset:512
	s_nop 0
	global_load_dwordx4 v[124:127], v[124:125], off offset:576
	s_waitcnt vmcnt(7)
	v_pk_fma_f32 v[92:93], v[92:93], v[158:159], v[96:97]
	v_lshl_add_u64 v[96:97], s[0:1], 0, v[204:205]
	v_lshl_add_u64 v[96:97], v[96:97], 0, v[172:173]
	s_waitcnt vmcnt(5)
	v_pk_fma_f32 v[78:79], v[78:79], v[164:165], v[106:107]
	v_pk_fma_f32 v[76:77], v[76:77], v[166:167], v[104:105]
	global_store_dwordx4 v[96:97], v[76:79], off offset:512
	s_waitcnt vmcnt(5)
	v_pk_fma_f32 v[74:75], v[74:75], v[168:169], v[110:111]
	v_pk_fma_f32 v[72:73], v[72:73], v[170:171], v[108:109]
	v_lshl_add_u64 v[76:77], s[0:1], 0, v[178:179]
	v_pk_fma_f32 v[94:95], v[94:95], v[156:157], v[98:99]
	v_pk_fma_f32 v[90:91], v[90:91], v[160:161], v[102:103]
	v_pk_fma_f32 v[88:89], v[88:89], v[162:163], v[100:101]
	global_store_dwordx4 v[96:97], v[72:75], off offset:576
	v_lshl_add_u64 v[76:77], v[76:77], 0, v[172:173]
	global_store_dwordx4 v[96:97], v[92:95], off
	s_waitcnt vmcnt(6)
	v_pk_fma_f32 v[74:75], v[86:87], v[156:157], v[114:115]
	v_pk_fma_f32 v[72:73], v[84:85], v[158:159], v[112:113]
	global_store_dwordx4 v[96:97], v[88:91], off offset:64
	global_store_dwordx4 v[76:77], v[72:75], off
	s_waitcnt vmcnt(6)
	v_pk_fma_f32 v[70:71], v[70:71], v[164:165], v[122:123]
	v_pk_fma_f32 v[68:69], v[68:69], v[166:167], v[120:121]
	v_pk_fma_f32 v[74:75], v[82:83], v[160:161], v[118:119]
	v_pk_fma_f32 v[72:73], v[80:81], v[162:163], v[116:117]
	s_waitcnt vmcnt(5)
	v_pk_fma_f32 v[66:67], v[66:67], v[168:169], v[126:127]
	v_pk_fma_f32 v[64:65], v[64:65], v[170:171], v[124:125]
	v_lshl_add_u64 v[96:97], v[176:177], 0, s[20:21]
	global_store_dwordx4 v[76:77], v[72:75], off offset:64
	global_store_dwordx4 v[76:77], v[68:71], off offset:512
	global_store_dwordx4 v[76:77], v[64:67], off offset:576
	v_lshl_add_u64 v[76:77], v[174:175], 0, v[96:97]
	global_load_dwordx4 v[64:67], v[76:77], off
	global_load_dwordx4 v[68:71], v[76:77], off offset:64
	global_load_dwordx4 v[72:75], v[76:77], off offset:512
	s_nop 0
	global_load_dwordx4 v[76:79], v[76:77], off offset:576
	v_lshl_add_u64 v[98:99], v[176:177], 0, s[22:23]
	v_lshl_add_u64 v[92:93], v[174:175], 0, v[98:99]
	global_load_dwordx4 v[80:83], v[92:93], off
	global_load_dwordx4 v[84:87], v[92:93], off offset:64
	global_load_dwordx4 v[88:91], v[92:93], off offset:512
	s_nop 0
	global_load_dwordx4 v[92:95], v[92:93], off offset:576
	s_waitcnt vmcnt(7)
	v_pk_fma_f32 v[60:61], v[60:61], v[158:159], v[64:65]
	v_lshl_add_u64 v[64:65], s[0:1], 0, v[96:97]
	v_lshl_add_u64 v[64:65], v[64:65], 0, v[172:173]
	s_waitcnt vmcnt(5)
	v_pk_fma_f32 v[46:47], v[46:47], v[164:165], v[74:75]
	v_pk_fma_f32 v[44:45], v[44:45], v[166:167], v[72:73]
	global_store_dwordx4 v[64:65], v[44:47], off offset:512
	s_waitcnt vmcnt(5)
	v_pk_fma_f32 v[42:43], v[42:43], v[168:169], v[78:79]
	v_pk_fma_f32 v[40:41], v[40:41], v[170:171], v[76:77]
	v_lshl_add_u64 v[44:45], s[0:1], 0, v[98:99]
	global_store_dwordx4 v[64:65], v[40:43], off offset:576
	v_lshl_add_u64 v[44:45], v[44:45], 0, v[172:173]
	v_pk_fma_f32 v[62:63], v[62:63], v[156:157], v[66:67]
	s_waitcnt vmcnt(5)
	v_pk_fma_f32 v[42:43], v[54:55], v[156:157], v[82:83]
	v_pk_fma_f32 v[40:41], v[52:53], v[158:159], v[80:81]
	v_pk_fma_f32 v[58:59], v[58:59], v[160:161], v[70:71]
	v_pk_fma_f32 v[56:57], v[56:57], v[162:163], v[68:69]
	global_store_dwordx4 v[44:45], v[40:43], off
	s_waitcnt vmcnt(4)
	v_pk_fma_f32 v[38:39], v[38:39], v[164:165], v[90:91]
	v_pk_fma_f32 v[36:37], v[36:37], v[166:167], v[88:89]
	v_pk_fma_f32 v[42:43], v[50:51], v[160:161], v[86:87]
	v_pk_fma_f32 v[40:41], v[48:49], v[162:163], v[84:85]
	s_waitcnt vmcnt(3)
	v_pk_fma_f32 v[34:35], v[34:35], v[168:169], v[94:95]
	v_pk_fma_f32 v[32:33], v[32:33], v[170:171], v[92:93]
	v_lshl_add_u64 v[66:67], v[176:177], 0, s[24:25]
	global_store_dwordx4 v[64:65], v[60:63], off
	global_store_dwordx4 v[64:65], v[56:59], off offset:64
	global_store_dwordx4 v[44:45], v[40:43], off offset:64
	global_store_dwordx4 v[44:45], v[36:39], off offset:512
	global_store_dwordx4 v[44:45], v[32:35], off offset:576
	v_lshl_add_u64 v[64:65], v[176:177], 0, s[26:27]
	v_lshl_add_u64 v[36:37], v[174:175], 0, v[64:65]
	v_lshl_add_u64 v[32:33], v[174:175], 0, v[66:67]
	global_load_dwordx4 v[48:51], v[32:33], off
	global_load_dwordx4 v[60:63], v[32:33], off offset:64
	global_load_dwordx4 v[56:59], v[32:33], off offset:512
	global_load_dwordx4 v[52:55], v[32:33], off offset:576
	s_nop 0
	global_load_dwordx4 v[32:35], v[36:37], off
	global_load_dwordx4 v[44:47], v[36:37], off offset:64
	global_load_dwordx4 v[40:43], v[36:37], off offset:512
	s_nop 0
	global_load_dwordx4 v[36:39], v[36:37], off offset:576
	s_waitcnt vmcnt(7)
	v_pk_fma_f32 v[28:29], v[28:29], v[158:159], v[48:49]
	v_lshl_add_u64 v[48:49], s[0:1], 0, v[66:67]
	v_lshl_add_u64 v[48:49], v[48:49], 0, v[172:173]
	s_waitcnt vmcnt(5)
	v_pk_fma_f32 v[18:19], v[18:19], v[164:165], v[58:59]
	v_pk_fma_f32 v[16:17], v[16:17], v[166:167], v[56:57]
	global_store_dwordx4 v[48:49], v[16:19], off offset:512
	s_waitcnt vmcnt(5)
	v_pk_fma_f32 v[10:11], v[10:11], v[168:169], v[54:55]
	v_pk_fma_f32 v[8:9], v[8:9], v[170:171], v[52:53]
	v_lshl_add_u64 v[16:17], s[0:1], 0, v[64:65]
	global_store_dwordx4 v[48:49], v[8:11], off offset:576
	v_lshl_add_u64 v[16:17], v[16:17], 0, v[172:173]
	v_pk_fma_f32 v[30:31], v[30:31], v[156:157], v[50:51]
	s_waitcnt vmcnt(5)
	v_pk_fma_f32 v[10:11], v[22:23], v[156:157], v[34:35]
	v_pk_fma_f32 v[8:9], v[20:21], v[158:159], v[32:33]
	v_pk_fma_f32 v[26:27], v[26:27], v[160:161], v[62:63]
	v_pk_fma_f32 v[24:25], v[24:25], v[162:163], v[60:61]
	global_store_dwordx4 v[16:17], v[8:11], off
	s_waitcnt vmcnt(4)
	v_pk_fma_f32 v[6:7], v[6:7], v[164:165], v[42:43]
	v_pk_fma_f32 v[4:5], v[4:5], v[166:167], v[40:41]
	v_pk_fma_f32 v[10:11], v[14:15], v[160:161], v[46:47]
	v_pk_fma_f32 v[8:9], v[12:13], v[162:163], v[44:45]
	s_waitcnt vmcnt(3)
	v_pk_fma_f32 v[2:3], v[2:3], v[168:169], v[38:39]
	v_pk_fma_f32 v[0:1], v[0:1], v[170:171], v[36:37]
	global_store_dwordx4 v[48:49], v[28:31], off
	global_store_dwordx4 v[48:49], v[24:27], off offset:64
	global_store_dwordx4 v[16:17], v[8:11], off offset:64
	global_store_dwordx4 v[16:17], v[4:7], off offset:512
	global_store_dwordx4 v[16:17], v[0:3], off offset:576
	s_waitcnt vmcnt(0)
	s_barrier
	s_and_saveexec_b64 s[46:47], s[4:5]
	s_cbranch_execz .LBB0_2375
	s_lshl_b32 s48, s44, 2
	s_ashr_i32 s49, s48, 31
	s_lshl_b64 s[48:49], s[48:49], 2
	s_add_u32 s48, s72, s48
	s_addc_u32 s49, s73, s49
	s_getreg_b32 s45, hwreg(HW_REG_XCC_ID, 0, 4)
	global_load_dwordx4 v[0:3], v131, s[48:49]
	s_and_b32 s45, s45, 15
	s_add_i32 s45, s45, 1
	s_waitcnt vmcnt(0)
	v_cmp_ne_u32_e32 vcc, s45, v2
	s_nop 1
	v_cndmask_b32_e64 v2, 0, 1, vcc
	v_cmp_ne_u32_e32 vcc, s45, v3
	v_lshlrev_b32_e32 v2, 2, v2
	s_nop 0
	v_cndmask_b32_e64 v3, 0, 1, vcc
	v_cmp_ne_u32_e32 vcc, s45, v1
	v_lshlrev_b32_e32 v3, 3, v3
	v_or_b32_e32 v2, v3, v2
	v_cndmask_b32_e64 v1, 0, 1, vcc
	v_cmp_ne_u32_e32 vcc, s45, v0
	v_lshlrev_b32_e32 v1, 1, v1
	s_nop 0
	v_cndmask_b32_e64 v0, 0, 1, vcc
	v_or_b32_e32 v0, v0, v1
	v_and_b32_e32 v0, 3, v0
	v_or_b32_e32 v0, v0, v2
	v_and_b32_e32 v0, 15, v0
	v_cmp_eq_u32_e32 vcc, 0, v0
	s_cbranch_vccnz .LBB0_2364
	buffer_wbl2 sc1
	s_waitcnt vmcnt(0)

.LBB0_2522:
	v_lshl_or_b32 v160, s60, 8, v177
	v_add_u32_e32 v144, 0x2000, v160
	v_ashrrev_i32_e32 v145, 31, v144
	s_ashr_i32 s30, s61, 3
	v_lshlrev_b64 v[148:149], 2, v[144:145]
	s_add_i32 s39, s30, 64
	v_lshl_add_u64 v[152:153], s[2:3], 0, v[148:149]
	v_lshl_add_u64 v[144:145], s[16:17], 0, v[148:149]
	v_mad_i64_i32 v[148:149], s[64:65], s39, v181, v[152:153]
	global_load_dwordx4 v[144:147], v[144:145], off
	s_add_i32 s38, s30, 0x48
	s_add_i32 s37, s30, 0x50
	s_add_i32 s36, s30, 0x58
	s_add_i32 s35, s30, 0x60
	s_add_i32 s34, s30, 0x68
	s_add_i32 s31, s30, 0x70
	s_addk_i32 s30, 0x78
	s_lshl_b32 s62, s61, 8
	global_load_dwordx4 v[148:151], v[148:149], off
	v_mad_i64_i32 v[182:183], s[64:65], s38, v181, v[152:153]
	global_load_dwordx4 v[182:185], v[182:183], off
	v_mad_i64_i32 v[186:187], s[64:65], s37, v181, v[152:153]
	global_load_dwordx4 v[186:189], v[186:187], off
	v_mad_i64_i32 v[190:191], s[64:65], s36, v181, v[152:153]
	global_load_dwordx4 v[190:193], v[190:191], off
	v_mad_i64_i32 v[200:201], s[64:65], s35, v181, v[152:153]
	global_load_dwordx4 v[200:203], v[200:201], off
	v_mad_i64_i32 v[204:205], s[64:65], s34, v181, v[152:153]
	global_load_dwordx4 v[204:207], v[204:205], off
	v_mad_i64_i32 v[208:209], s[64:65], s31, v181, v[152:153]
	global_load_dwordx4 v[208:211], v[208:209], off
	v_mad_i64_i32 v[216:217], s[64:65], s30, v181, v[152:153]
	global_load_dwordx4 v[216:219], v[216:217], off
	v_ashrrev_i32_e32 v161, 31, v160
	v_readfirstlane_b32 s63, v168
	s_waitcnt vmcnt(7)
	v_pk_add_f32 v[148:149], v[144:145], v[148:149]
	v_pk_add_f32 v[150:151], v[146:147], v[150:151]
	s_waitcnt vmcnt(6)
	v_pk_add_f32 v[148:149], v[148:149], v[182:183]
	v_pk_add_f32 v[150:151], v[150:151], v[184:185]
	s_waitcnt vmcnt(5)
	v_pk_add_f32 v[148:149], v[148:149], v[186:187]
	v_pk_add_f32 v[150:151], v[150:151], v[188:189]
	s_waitcnt vmcnt(4)
	v_pk_add_f32 v[148:149], v[148:149], v[190:191]
	v_pk_add_f32 v[150:151], v[150:151], v[192:193]
	s_waitcnt vmcnt(3)
	v_pk_add_f32 v[148:149], v[148:149], v[200:201]
	v_pk_add_f32 v[150:151], v[150:151], v[202:203]
	s_waitcnt vmcnt(2)
	v_pk_add_f32 v[148:149], v[148:149], v[204:205]
	v_pk_add_f32 v[150:151], v[150:151], v[206:207]
	s_waitcnt vmcnt(1)
	v_pk_add_f32 v[148:149], v[148:149], v[208:209]
	v_pk_add_f32 v[150:151], v[150:151], v[210:211]
	s_waitcnt vmcnt(0)
	v_pk_add_f32 v[146:147], v[150:151], v[218:219]
	v_pk_add_f32 v[148:149], v[148:149], v[216:217]
	v_pk_mul_f32 v[144:145], v[146:147], 0.5 op_sel_hi:[1, 0]
	v_pk_mul_f32 v[146:147], v[148:149], 0.5 op_sel_hi:[1, 0]
	v_add_u32_e32 v148, 0x2010, v160
	v_ashrrev_i32_e32 v149, 31, v148
	v_lshlrev_b64 v[152:153], 2, v[148:149]
	v_lshl_add_u64 v[156:157], s[2:3], 0, v[152:153]
	v_lshl_add_u64 v[148:149], s[16:17], 0, v[152:153]
	v_mad_i64_i32 v[152:153], s[64:65], s39, v181, v[156:157]
	global_load_dwordx4 v[148:151], v[148:149], off
	global_load_dwordx4 v[152:155], v[152:153], off
	v_mad_i64_i32 v[182:183], s[64:65], s38, v181, v[156:157]
	global_load_dwordx4 v[182:185], v[182:183], off
	v_mad_i64_i32 v[186:187], s[64:65], s37, v181, v[156:157]
	global_load_dwordx4 v[186:189], v[186:187], off
	v_mad_i64_i32 v[190:191], s[64:65], s36, v181, v[156:157]
	global_load_dwordx4 v[190:193], v[190:191], off
	v_mad_i64_i32 v[200:201], s[64:65], s35, v181, v[156:157]
	global_load_dwordx4 v[200:203], v[200:201], off
	v_mad_i64_i32 v[204:205], s[64:65], s34, v181, v[156:157]
	global_load_dwordx4 v[204:207], v[204:205], off
	v_mad_i64_i32 v[208:209], s[64:65], s31, v181, v[156:157]
	global_load_dwordx4 v[208:211], v[208:209], off
	v_mad_i64_i32 v[216:217], s[64:65], s30, v181, v[156:157]
	global_load_dwordx4 v[216:219], v[216:217], off
	s_waitcnt vmcnt(7)
	v_pk_add_f32 v[152:153], v[148:149], v[152:153]
	v_pk_add_f32 v[154:155], v[150:151], v[154:155]
	s_waitcnt vmcnt(6)
	v_pk_add_f32 v[152:153], v[152:153], v[182:183]
	v_pk_add_f32 v[154:155], v[154:155], v[184:185]
	s_waitcnt vmcnt(5)
	v_pk_add_f32 v[152:153], v[152:153], v[186:187]
	v_pk_add_f32 v[154:155], v[154:155], v[188:189]
	s_waitcnt vmcnt(4)
	v_pk_add_f32 v[152:153], v[152:153], v[190:191]
	v_pk_add_f32 v[154:155], v[154:155], v[192:193]
	s_waitcnt vmcnt(3)
	v_pk_add_f32 v[152:153], v[152:153], v[200:201]
	v_pk_add_f32 v[154:155], v[154:155], v[202:203]
	s_waitcnt vmcnt(2)
	v_pk_add_f32 v[152:153], v[152:153], v[204:205]
	v_pk_add_f32 v[154:155], v[154:155], v[206:207]
	s_waitcnt vmcnt(1)
	v_pk_add_f32 v[152:153], v[152:153], v[208:209]
	v_pk_add_f32 v[154:155], v[154:155], v[210:211]
	s_waitcnt vmcnt(0)
	v_pk_add_f32 v[150:151], v[154:155], v[218:219]
	v_pk_add_f32 v[152:153], v[152:153], v[216:217]
	v_pk_mul_f32 v[148:149], v[150:151], 0.5 op_sel_hi:[1, 0]
	v_pk_mul_f32 v[150:151], v[152:153], 0.5 op_sel_hi:[1, 0]
	v_add_u32_e32 v152, 0x2080, v160
	v_ashrrev_i32_e32 v153, 31, v152
	v_lshlrev_b64 v[156:157], 2, v[152:153]
	v_lshl_add_u64 v[162:163], s[2:3], 0, v[156:157]
	v_lshl_add_u64 v[152:153], s[16:17], 0, v[156:157]
	v_mad_i64_i32 v[156:157], s[64:65], s39, v181, v[162:163]
	global_load_dwordx4 v[152:155], v[152:153], off
	global_load_dwordx4 v[156:159], v[156:157], off
	v_mad_i64_i32 v[182:183], s[64:65], s38, v181, v[162:163]
	global_load_dwordx4 v[182:185], v[182:183], off
	v_mad_i64_i32 v[186:187], s[64:65], s37, v181, v[162:163]
	global_load_dwordx4 v[186:189], v[186:187], off
	v_mad_i64_i32 v[190:191], s[64:65], s36, v181, v[162:163]
	global_load_dwordx4 v[190:193], v[190:191], off
	v_mad_i64_i32 v[200:201], s[64:65], s35, v181, v[162:163]
	global_load_dwordx4 v[200:203], v[200:201], off
	v_mad_i64_i32 v[204:205], s[64:65], s34, v181, v[162:163]
	global_load_dwordx4 v[204:207], v[204:205], off
	v_mad_i64_i32 v[208:209], s[64:65], s31, v181, v[162:163]
	global_load_dwordx4 v[208:211], v[208:209], off
	v_mad_i64_i32 v[216:217], s[64:65], s30, v181, v[162:163]
	global_load_dwordx4 v[216:219], v[216:217], off
	s_waitcnt vmcnt(7)
	v_pk_add_f32 v[156:157], v[152:153], v[156:157]
	v_pk_add_f32 v[158:159], v[154:155], v[158:159]
	s_waitcnt vmcnt(6)
	v_pk_add_f32 v[156:157], v[156:157], v[182:183]
	v_pk_add_f32 v[158:159], v[158:159], v[184:185]
	s_waitcnt vmcnt(5)
	v_pk_add_f32 v[156:157], v[156:157], v[186:187]
	v_pk_add_f32 v[158:159], v[158:159], v[188:189]
	s_waitcnt vmcnt(4)
	v_pk_add_f32 v[156:157], v[156:157], v[190:191]
	v_pk_add_f32 v[158:159], v[158:159], v[192:193]
	s_waitcnt vmcnt(3)
	v_pk_add_f32 v[156:157], v[156:157], v[200:201]
	v_pk_add_f32 v[158:159], v[158:159], v[202:203]
	s_waitcnt vmcnt(2)
	v_pk_add_f32 v[156:157], v[156:157], v[204:205]
	v_pk_add_f32 v[158:159], v[158:159], v[206:207]
	s_waitcnt vmcnt(1)
	v_pk_add_f32 v[156:157], v[156:157], v[208:209]
	v_pk_add_f32 v[158:159], v[158:159], v[210:211]
	s_waitcnt vmcnt(0)
	v_pk_add_f32 v[154:155], v[158:159], v[218:219]
	v_pk_add_f32 v[156:157], v[156:157], v[216:217]
	v_pk_mul_f32 v[152:153], v[154:155], 0.5 op_sel_hi:[1, 0]
	v_pk_mul_f32 v[154:155], v[156:157], 0.5 op_sel_hi:[1, 0]
	v_add_u32_e32 v156, 0x2090, v160
	v_ashrrev_i32_e32 v157, 31, v156
	v_lshlrev_b64 v[162:163], 2, v[156:157]
	v_lshl_add_u64 v[166:167], s[2:3], 0, v[162:163]
	v_lshl_add_u64 v[156:157], s[16:17], 0, v[162:163]
	v_mad_i64_i32 v[162:163], s[64:65], s39, v181, v[166:167]
	global_load_dwordx4 v[156:159], v[156:157], off
	global_load_dwordx4 v[162:165], v[162:163], off
	v_mad_i64_i32 v[182:183], s[38:39], s38, v181, v[166:167]
	global_load_dwordx4 v[182:185], v[182:183], off
	v_mad_i64_i32 v[186:187], s[38:39], s37, v181, v[166:167]
	global_load_dwordx4 v[186:189], v[186:187], off
	v_mad_i64_i32 v[190:191], s[36:37], s36, v181, v[166:167]
	global_load_dwordx4 v[190:193], v[190:191], off
	v_mad_i64_i32 v[200:201], s[36:37], s35, v181, v[166:167]
	global_load_dwordx4 v[200:203], v[200:201], off
	v_mad_i64_i32 v[204:205], s[34:35], s34, v181, v[166:167]
	global_load_dwordx4 v[204:207], v[204:205], off
	v_mad_i64_i32 v[208:209], s[34:35], s31, v181, v[166:167]
	global_load_dwordx4 v[208:211], v[208:209], off
	v_mad_i64_i32 v[216:217], s[30:31], s30, v181, v[166:167]
	global_load_dwordx4 v[216:219], v[216:217], off
	v_lshlrev_b64 v[160:161], 2, v[160:161]
	s_waitcnt vmcnt(7)
	v_pk_add_f32 v[162:163], v[156:157], v[162:163]
	v_pk_add_f32 v[164:165], v[158:159], v[164:165]
	s_waitcnt vmcnt(6)
	v_pk_add_f32 v[162:163], v[162:163], v[182:183]
	v_pk_add_f32 v[164:165], v[164:165], v[184:185]
	s_waitcnt vmcnt(5)
	v_pk_add_f32 v[162:163], v[162:163], v[186:187]
	v_pk_add_f32 v[164:165], v[164:165], v[188:189]
	s_waitcnt vmcnt(4)
	v_pk_add_f32 v[162:163], v[162:163], v[190:191]
	v_pk_add_f32 v[164:165], v[164:165], v[192:193]
	s_waitcnt vmcnt(3)
	v_pk_add_f32 v[162:163], v[162:163], v[200:201]
	v_pk_add_f32 v[164:165], v[164:165], v[202:203]
	s_waitcnt vmcnt(2)
	v_pk_add_f32 v[162:163], v[162:163], v[204:205]
	v_pk_add_f32 v[164:165], v[164:165], v[206:207]
	s_waitcnt vmcnt(1)
	v_pk_add_f32 v[162:163], v[162:163], v[208:209]
	v_pk_add_f32 v[164:165], v[164:165], v[210:211]
	v_add_u32_e32 v166, s62, v169
	v_ashrrev_i32_e32 v167, 31, v166
	v_or_b32_e32 v198, 16, v166
	v_ashrrev_i32_e32 v199, 31, v198
	v_lshlrev_b64 v[214:215], 12, v[198:199]
	s_waitcnt vmcnt(0)
	v_pk_add_f32 v[158:159], v[164:165], v[218:219]
	v_pk_add_f32 v[162:163], v[162:163], v[216:217]
	v_pk_mul_f32 v[156:157], v[158:159], 0.5 op_sel_hi:[1, 0]
	v_pk_mul_f32 v[158:159], v[162:163], 0.5 op_sel_hi:[1, 0]
	v_lshl_add_u64 v[162:163], s[10:11], 0, v[160:161]
	v_lshlrev_b64 v[164:165], 12, v[166:167]
	v_lshl_add_u64 v[194:195], v[162:163], 0, v[164:165]
	global_load_dwordx4 v[182:185], v[194:195], off
	global_load_dwordx4 v[186:189], v[194:195], off offset:64
	global_load_dwordx4 v[190:193], v[194:195], off offset:512
	s_nop 0
	global_load_dwordx4 v[194:197], v[194:195], off offset:576
	v_lshl_add_u64 v[210:211], v[162:163], 0, v[214:215]
	global_load_dwordx4 v[198:201], v[210:211], off
	global_load_dwordx4 v[202:205], v[210:211], off offset:64
	global_load_dwordx4 v[206:209], v[210:211], off offset:512
	s_nop 0
	global_load_dwordx4 v[210:213], v[210:211], off offset:576
	s_waitcnt vmcnt(7)
	v_pk_fma_f32 v[124:125], v[124:125], v[146:147], v[182:183]
	v_lshl_add_u64 v[182:183], s[10:11], 0, v[164:165]
	v_lshl_add_u64 v[182:183], v[182:183], 0, v[160:161]
	s_waitcnt vmcnt(5)
	v_pk_fma_f32 v[110:111], v[110:111], v[152:153], v[192:193]
	v_pk_fma_f32 v[108:109], v[108:109], v[154:155], v[190:191]
	global_store_dwordx4 v[182:183], v[108:111], off offset:512
	s_waitcnt vmcnt(1)
	v_pk_fma_f32 v[98:99], v[98:99], v[156:157], v[212:213]
	v_pk_fma_f32 v[96:97], v[96:97], v[158:159], v[210:211]
	v_lshl_add_u64 v[108:109], s[10:11], 0, v[214:215]
	v_lshl_add_u64 v[108:109], v[108:109], 0, v[160:161]
	v_pk_fma_f32 v[106:107], v[106:107], v[156:157], v[196:197]
	v_pk_fma_f32 v[104:105], v[104:105], v[158:159], v[194:195]
	global_store_dwordx4 v[108:109], v[96:99], off offset:576
	v_pk_fma_f32 v[126:127], v[126:127], v[144:145], v[184:185]
	v_pk_fma_f32 v[122:123], v[122:123], v[148:149], v[188:189]
	v_or_b32_e32 v96, 32, v166
	v_pk_fma_f32 v[120:121], v[120:121], v[150:151], v[186:187]
	global_store_dwordx4 v[182:183], v[104:107], off offset:576
	v_ashrrev_i32_e32 v97, 31, v96
	global_store_dwordx4 v[182:183], v[124:127], off
	v_pk_fma_f32 v[106:107], v[118:119], v[144:145], v[200:201]
	v_pk_fma_f32 v[104:105], v[116:117], v[146:147], v[198:199]
	global_store_dwordx4 v[182:183], v[120:123], off offset:64
	global_store_dwordx4 v[108:109], v[104:107], off
	v_pk_fma_f32 v[102:103], v[102:103], v[152:153], v[208:209]
	v_pk_fma_f32 v[100:101], v[100:101], v[154:155], v[206:207]
	v_pk_fma_f32 v[106:107], v[114:115], v[148:149], v[204:205]
	v_pk_fma_f32 v[104:105], v[112:113], v[150:151], v[202:203]
	v_lshlrev_b64 v[182:183], 12, v[96:97]
	v_or_b32_e32 v112, 48, v166
	global_store_dwordx4 v[108:109], v[104:107], off offset:64
	global_store_dwordx4 v[108:109], v[100:103], off offset:512
	v_lshl_add_u64 v[108:109], v[162:163], 0, v[182:183]
	v_ashrrev_i32_e32 v113, 31, v112
	global_load_dwordx4 v[96:99], v[108:109], off
	global_load_dwordx4 v[100:103], v[108:109], off offset:64
	global_load_dwordx4 v[104:107], v[108:109], off offset:512
	s_nop 0
	global_load_dwordx4 v[108:111], v[108:109], off offset:576
	v_lshlrev_b64 v[166:167], 12, v[112:113]
	v_lshl_add_u64 v[124:125], v[162:163], 0, v[166:167]
	global_load_dwordx4 v[112:115], v[124:125], off
	global_load_dwordx4 v[116:119], v[124:125], off offset:64
	global_load_dwordx4 v[120:123], v[124:125], off offset:512
	s_nop 0
	global_load_dwordx4 v[124:127], v[124:125], off offset:576
	s_waitcnt vmcnt(7)
	v_pk_fma_f32 v[92:93], v[92:93], v[146:147], v[96:97]
	v_lshl_add_u64 v[96:97], s[10:11], 0, v[182:183]
	v_lshl_add_u64 v[96:97], v[96:97], 0, v[160:161]
	s_waitcnt vmcnt(5)
	v_pk_fma_f32 v[78:79], v[78:79], v[152:153], v[106:107]
	v_pk_fma_f32 v[76:77], v[76:77], v[154:155], v[104:105]
	global_store_dwordx4 v[96:97], v[76:79], off offset:512
	s_waitcnt vmcnt(5)
	v_pk_fma_f32 v[74:75], v[74:75], v[156:157], v[110:111]
	v_pk_fma_f32 v[72:73], v[72:73], v[158:159], v[108:109]
	v_lshl_add_u64 v[76:77], s[10:11], 0, v[166:167]
	v_pk_fma_f32 v[94:95], v[94:95], v[144:145], v[98:99]
	v_pk_fma_f32 v[90:91], v[90:91], v[148:149], v[102:103]
	v_pk_fma_f32 v[88:89], v[88:89], v[150:151], v[100:101]
	global_store_dwordx4 v[96:97], v[72:75], off offset:576
	v_lshl_add_u64 v[76:77], v[76:77], 0, v[160:161]
	global_store_dwordx4 v[96:97], v[92:95], off
	s_waitcnt vmcnt(6)
	v_pk_fma_f32 v[74:75], v[86:87], v[144:145], v[114:115]
	v_pk_fma_f32 v[72:73], v[84:85], v[146:147], v[112:113]
	global_store_dwordx4 v[96:97], v[88:91], off offset:64
	global_store_dwordx4 v[76:77], v[72:75], off
	s_waitcnt vmcnt(6)
	v_pk_fma_f32 v[70:71], v[70:71], v[152:153], v[122:123]
	v_pk_fma_f32 v[68:69], v[68:69], v[154:155], v[120:121]
	v_pk_fma_f32 v[74:75], v[82:83], v[148:149], v[118:119]
	v_pk_fma_f32 v[72:73], v[80:81], v[150:151], v[116:117]
	s_waitcnt vmcnt(5)
	v_pk_fma_f32 v[66:67], v[66:67], v[156:157], v[126:127]
	v_pk_fma_f32 v[64:65], v[64:65], v[158:159], v[124:125]
	v_lshl_add_u64 v[96:97], v[164:165], 0, s[8:9]
	global_store_dwordx4 v[76:77], v[72:75], off offset:64
	global_store_dwordx4 v[76:77], v[68:71], off offset:512
	global_store_dwordx4 v[76:77], v[64:67], off offset:576
	v_lshl_add_u64 v[76:77], v[162:163], 0, v[96:97]
	global_load_dwordx4 v[64:67], v[76:77], off
	global_load_dwordx4 v[68:71], v[76:77], off offset:64
	global_load_dwordx4 v[72:75], v[76:77], off offset:512
	s_nop 0
	global_load_dwordx4 v[76:79], v[76:77], off offset:576
	v_lshl_add_u64 v[98:99], v[164:165], 0, s[18:19]
	v_lshl_add_u64 v[92:93], v[162:163], 0, v[98:99]
	global_load_dwordx4 v[80:83], v[92:93], off
	global_load_dwordx4 v[84:87], v[92:93], off offset:64
	global_load_dwordx4 v[88:91], v[92:93], off offset:512
	s_nop 0
	global_load_dwordx4 v[92:95], v[92:93], off offset:576
	s_waitcnt vmcnt(7)
	v_pk_fma_f32 v[60:61], v[60:61], v[146:147], v[64:65]
	v_lshl_add_u64 v[64:65], s[10:11], 0, v[96:97]
	v_lshl_add_u64 v[64:65], v[64:65], 0, v[160:161]
	s_waitcnt vmcnt(5)
	v_pk_fma_f32 v[46:47], v[46:47], v[152:153], v[74:75]
	v_pk_fma_f32 v[44:45], v[44:45], v[154:155], v[72:73]
	global_store_dwordx4 v[64:65], v[44:47], off offset:512
	s_waitcnt vmcnt(5)
	v_pk_fma_f32 v[42:43], v[42:43], v[156:157], v[78:79]
	v_pk_fma_f32 v[40:41], v[40:41], v[158:159], v[76:77]
	v_lshl_add_u64 v[44:45], s[10:11], 0, v[98:99]
	v_pk_fma_f32 v[62:63], v[62:63], v[144:145], v[66:67]
	v_pk_fma_f32 v[58:59], v[58:59], v[148:149], v[70:71]
	v_pk_fma_f32 v[56:57], v[56:57], v[150:151], v[68:69]
	global_store_dwordx4 v[64:65], v[40:43], off offset:576
	v_lshl_add_u64 v[44:45], v[44:45], 0, v[160:161]
	global_store_dwordx4 v[64:65], v[60:63], off
	s_waitcnt vmcnt(6)
	v_pk_fma_f32 v[42:43], v[54:55], v[144:145], v[82:83]
	v_pk_fma_f32 v[40:41], v[52:53], v[146:147], v[80:81]
	global_store_dwordx4 v[64:65], v[56:59], off offset:64
	global_store_dwordx4 v[44:45], v[40:43], off
	s_waitcnt vmcnt(6)
	v_pk_fma_f32 v[38:39], v[38:39], v[152:153], v[90:91]
	v_pk_fma_f32 v[36:37], v[36:37], v[154:155], v[88:89]
	v_pk_fma_f32 v[42:43], v[50:51], v[148:149], v[86:87]
	v_pk_fma_f32 v[40:41], v[48:49], v[150:151], v[84:85]
	s_waitcnt vmcnt(5)
	v_pk_fma_f32 v[34:35], v[34:35], v[156:157], v[94:95]
	v_pk_fma_f32 v[32:33], v[32:33], v[158:159], v[92:93]
	v_lshl_add_u64 v[64:65], v[164:165], 0, s[20:21]
	global_store_dwordx4 v[44:45], v[40:43], off offset:64
	global_store_dwordx4 v[44:45], v[36:39], off offset:512
	global_store_dwordx4 v[44:45], v[32:35], off offset:576
	v_lshl_add_u64 v[44:45], v[162:163], 0, v[64:65]
	global_load_dwordx4 v[32:35], v[44:45], off
	global_load_dwordx4 v[36:39], v[44:45], off offset:64
	global_load_dwordx4 v[40:43], v[44:45], off offset:512
	s_nop 0
	global_load_dwordx4 v[44:47], v[44:45], off offset:576
	v_lshl_add_u64 v[66:67], v[164:165], 0, s[22:23]
	v_lshl_add_u64 v[60:61], v[162:163], 0, v[66:67]
	global_load_dwordx4 v[48:51], v[60:61], off
	global_load_dwordx4 v[52:55], v[60:61], off offset:64
	global_load_dwordx4 v[56:59], v[60:61], off offset:512
	s_nop 0
	global_load_dwordx4 v[60:63], v[60:61], off offset:576
	s_waitcnt vmcnt(7)
	v_pk_fma_f32 v[28:29], v[28:29], v[146:147], v[32:33]
	v_lshl_add_u64 v[32:33], s[10:11], 0, v[64:65]
	v_lshl_add_u64 v[32:33], v[32:33], 0, v[160:161]
	s_waitcnt vmcnt(5)
	v_pk_fma_f32 v[18:19], v[18:19], v[152:153], v[42:43]
	v_pk_fma_f32 v[16:17], v[16:17], v[154:155], v[40:41]
	global_store_dwordx4 v[32:33], v[16:19], off offset:512
	s_waitcnt vmcnt(5)
	v_pk_fma_f32 v[10:11], v[10:11], v[156:157], v[46:47]
	v_pk_fma_f32 v[8:9], v[8:9], v[158:159], v[44:45]
	v_lshl_add_u64 v[16:17], s[10:11], 0, v[66:67]
	global_store_dwordx4 v[32:33], v[8:11], off offset:576
	v_lshl_add_u64 v[16:17], v[16:17], 0, v[160:161]
	v_pk_fma_f32 v[30:31], v[30:31], v[144:145], v[34:35]
	s_waitcnt vmcnt(5)
	v_pk_fma_f32 v[10:11], v[22:23], v[144:145], v[50:51]
	v_pk_fma_f32 v[8:9], v[20:21], v[146:147], v[48:49]
	v_pk_fma_f32 v[26:27], v[26:27], v[148:149], v[38:39]
	v_pk_fma_f32 v[24:25], v[24:25], v[150:151], v[36:37]
	global_store_dwordx4 v[16:17], v[8:11], off
	s_waitcnt vmcnt(4)
	v_pk_fma_f32 v[6:7], v[6:7], v[152:153], v[58:59]
	v_pk_fma_f32 v[4:5], v[4:5], v[154:155], v[56:57]
	v_pk_fma_f32 v[10:11], v[14:15], v[148:149], v[54:55]
	v_pk_fma_f32 v[8:9], v[12:13], v[150:151], v[52:53]
	s_waitcnt vmcnt(3)
	v_pk_fma_f32 v[2:3], v[2:3], v[156:157], v[62:63]
	v_pk_fma_f32 v[0:1], v[0:1], v[158:159], v[60:61]
	global_store_dwordx4 v[32:33], v[28:31], off
	global_store_dwordx4 v[32:33], v[24:27], off offset:64
	global_store_dwordx4 v[16:17], v[8:11], off offset:64
	global_store_dwordx4 v[16:17], v[4:7], off offset:512
	global_store_dwordx4 v[16:17], v[0:3], off offset:576
	s_waitcnt vmcnt(0)
	s_barrier
	s_and_saveexec_b64 s[30:31], s[0:1]
	s_cbranch_execz .LBB0_2536
	s_lshl_b32 s34, s61, 2
	s_ashr_i32 s35, s34, 31
	s_lshl_b64 s[34:35], s[34:35], 2
	s_add_u32 s34, s49, s34
	s_addc_u32 s35, s50, s35
	s_getreg_b32 s36, hwreg(HW_REG_XCC_ID, 0, 4)
	global_load_dwordx4 v[0:3], v129, s[34:35]
	s_and_b32 s34, s36, 15
	s_add_i32 s34, s34, 1
	s_waitcnt vmcnt(0)
	v_cmp_ne_u32_e32 vcc, s34, v2
	s_nop 1
	v_cndmask_b32_e64 v2, 0, 1, vcc
	v_cmp_ne_u32_e32 vcc, s34, v3
	v_lshlrev_b32_e32 v2, 2, v2
	s_nop 0
	v_cndmask_b32_e64 v3, 0, 1, vcc
	v_cmp_ne_u32_e32 vcc, s34, v1
	v_lshlrev_b32_e32 v3, 3, v3
	v_or_b32_e32 v2, v3, v2
	v_cndmask_b32_e64 v1, 0, 1, vcc
	v_cmp_ne_u32_e32 vcc, s34, v0
	v_lshlrev_b32_e32 v1, 1, v1
	s_nop 0
	v_cndmask_b32_e64 v0, 0, 1, vcc
	v_or_b32_e32 v0, v0, v1
	v_and_b32_e32 v0, 3, v0
	v_or_b32_e32 v0, v0, v2
	v_and_b32_e32 v0, 15, v0
	v_cmp_eq_u32_e32 vcc, 0, v0
	s_cbranch_vccnz .LBB0_2525
	buffer_wbl2 sc1
	s_waitcnt vmcnt(0)
